# E23: E14 + GEMM segment-edge edit: s_setprio 1 raised before the pre-MFMA barrier, s_setprio 0 dropped after the post-MFMA barrier, redundant post-barrier lgkmcnt(0) removed (20 sites)
# speedup vs baseline: 1.0072x; 1.0036x over previous
; #define PG8_STAGE(bufoff, gbase, voff) do { _Pragma("unroll") for (int _i = 0; _i < 2; ++_i) \
;         __builtin_amdgcn_global_load_lds((const unsigned*)((const char*)(gbase) + (voff)[_i]), (LAS unsigned*)(lds + (bufoff) + ldsw + _i * 8192), 16, 0, 0); } while (0)
; #define PG8_LDA(dst, b, h) do { _Pragma("unroll") for (int m = 0; m < 4; ++m) _Pragma("unroll") for (int k = 0; k < 2; ++k) dst[m][k] = *(const LAS bf16x8*)(lds + PG8_SA(b, h) + aoff + m * 2048 + k * 1024); } while (0)
; #define PG8_LDB(dst, b, h) do { _Pragma("unroll") for (int n = 0; n < 2; ++n) _Pragma("unroll") for (int k = 0; k < 2; ++k) dst[n][k] = *(const LAS bf16x8*)(lds + PG8_SB(b, h) + boff + n * 2048 + k * 1024); } while (0)
; #define PG8_MMA(ai, bj, At, Bt) do { __builtin_amdgcn_s_setprio(1); _Pragma("unroll") for (int m = 0; m < 4; ++m) _Pragma("unroll") for (int n = 0; n < 2; ++n) _Pragma("unroll") for (int k = 0; k < 2; ++k) \
;         acc[ai][bj][m][n] = __builtin_amdgcn_mfma_f32_16x16x32_bf16(Bt[n][k], At[m][k], acc[ai][bj][m][n], 0, 0, 0); __builtin_amdgcn_s_setprio(0); } while (0)
; #define PG8_WAIT_V(n) asm volatile("s_waitcnt vmcnt(" #n ")" ::: "memory")
; #define PG8_WAIT_L(n) asm volatile("s_waitcnt lgkmcnt(" #n ")" ::: "memory")
; #define PG8_BAR __builtin_amdgcn_s_barrier()
; #define PG8_SCHED __builtin_amdgcn_sched_barrier(0)
; template <class Epi>
; __device__ __forceinline__ void gemm_phase(LAS unsigned char* lds, const Gemm g, const StaticOrder& S, const Epi& E) {
;     ...
;             PG8_LDB(B0, 0, 0); PG8_LDB(B1, 0, 1); PG8_SCHED; PG8_LDA(At, 0, 0); PG8_STAGE(PG8_SA(1, 1), a1 + hstep, voffA);
;             PG8_WAIT_V(8); PG8_WAIT_L(0); PG8_BAR; PG8_MMA(0, 0, At, B0); PG8_MMA(0, 1, At, B1); PG8_BAR; PG8_SCHED;
;             PG8_LDA(At, 0, 1); PG8_STAGE(PG8_SB(0, 0), b2, voffB); PG8_STAGE(PG8_SB(0, 1), b2 + hstep, voffB); PG8_STAGE(PG8_SA(0, 0), a2, voffA);
;             PG8_WAIT_V(8); PG8_WAIT_L(0); PG8_BAR; PG8_MMA(1, 0, At, B0); PG8_MMA(1, 1, At, B1); PG8_BAR; PG8_SCHED;
.LBB0_191:
	s_add_u32 s22, s20, 0xfff80080
	s_addc_u32 s23, s21, -1
	s_add_i32 s55, 0, 0x10000
	s_cmp_eq_u32 s45, 28
	s_cselect_b32 s25, s15, s23
	s_cselect_b32 s24, s39, s22
	s_cselect_b32 s23, s13, s44
	s_cselect_b32 s22, s40, s41
	s_add_i32 s76, 0, 0x14000
	s_waitcnt lgkmcnt(0)
	v_add_u32_e32 v170, s55, v147
	v_add_u32_e32 v186, s76, v147
	ds_read_b128 v[132:135], v170
	ds_read_b128 v[162:165], v170 offset:1024
	ds_read_b128 v[166:169], v170 offset:2048
	ds_read_b128 v[170:173], v170 offset:3072
	ds_read_b128 v[174:177], v186
	ds_read_b128 v[178:181], v186 offset:1024
	ds_read_b128 v[182:185], v186 offset:2048
	ds_read_b128 v[186:189], v186 offset:3072
	v_lshl_add_u64 v[242:243], s[20:21], 0, v[158:159]
	s_add_i32 m0, s29, 0xc000
	ds_read_b128 v[190:193], v213
	ds_read_b128 v[214:217], v213 offset:1024
	ds_read_b128 v[218:221], v213 offset:2048
	ds_read_b128 v[222:225], v213 offset:3072
	ds_read_b128 v[226:229], v213 offset:4096
	ds_read_b128 v[230:233], v213 offset:5120
	ds_read_b128 v[234:237], v213 offset:6144
	ds_read_b128 v[238:241], v213 offset:7168
	global_load_lds_dwordx4 v[242:243], off
	v_lshl_add_u64 v[242:243], s[20:21], 0, v[160:161]
	s_add_i32 m0, s29, 0xe000
	s_nop 0
	global_load_lds_dwordx4 v[242:243], off
	s_waitcnt vmcnt(8)
	s_waitcnt lgkmcnt(0)
	s_setprio 1
	s_barrier
	v_mfma_f32_16x16x32_bf16 v[128:131], v[132:135], v[190:193], v[128:131]
	v_mfma_f32_16x16x32_bf16 v[124:127], v[166:169], v[190:193], v[124:127]
	v_mfma_f32_16x16x32_bf16 v[112:115], v[132:135], v[218:221], v[112:115]
	v_mfma_f32_16x16x32_bf16 v[108:111], v[166:169], v[218:221], v[108:111]
	v_mfma_f32_16x16x32_bf16 v[96:99], v[132:135], v[226:229], v[96:99]
	v_mfma_f32_16x16x32_bf16 v[92:95], v[166:169], v[226:229], v[92:95]
	v_mfma_f32_16x16x32_bf16 v[80:83], v[132:135], v[234:237], v[80:83]
	v_mfma_f32_16x16x32_bf16 v[76:79], v[166:169], v[234:237], v[76:79]
	v_mfma_f32_16x16x32_bf16 v[128:131], v[162:165], v[214:217], v[128:131]
	v_mfma_f32_16x16x32_bf16 v[124:127], v[170:173], v[214:217], v[124:127]
	v_mfma_f32_16x16x32_bf16 v[112:115], v[162:165], v[222:225], v[112:115]
	v_mfma_f32_16x16x32_bf16 v[108:111], v[170:173], v[222:225], v[108:111]
	v_mfma_f32_16x16x32_bf16 v[96:99], v[162:165], v[230:233], v[96:99]
	v_mfma_f32_16x16x32_bf16 v[92:95], v[170:173], v[230:233], v[92:95]
	v_mfma_f32_16x16x32_bf16 v[80:83], v[162:165], v[238:241], v[80:83]
	v_mfma_f32_16x16x32_bf16 v[76:79], v[170:173], v[238:241], v[76:79]
	s_setprio 0
	s_setprio 1
	v_mfma_f32_16x16x32_bf16 v[120:123], v[174:177], v[190:193], v[120:123]
	v_mfma_f32_16x16x32_bf16 v[116:119], v[182:185], v[190:193], v[116:119]
	v_mfma_f32_16x16x32_bf16 v[104:107], v[174:177], v[218:221], v[104:107]
	v_mfma_f32_16x16x32_bf16 v[100:103], v[182:185], v[218:221], v[100:103]
	v_mfma_f32_16x16x32_bf16 v[88:91], v[174:177], v[226:229], v[88:91]
	v_mfma_f32_16x16x32_bf16 v[84:87], v[182:185], v[226:229], v[84:87]
	v_mfma_f32_16x16x32_bf16 v[72:75], v[174:177], v[234:237], v[72:75]
	v_mfma_f32_16x16x32_bf16 v[68:71], v[182:185], v[234:237], v[68:71]
	v_mfma_f32_16x16x32_bf16 v[120:123], v[178:181], v[214:217], v[120:123]
	v_mfma_f32_16x16x32_bf16 v[116:119], v[186:189], v[214:217], v[116:119]
	v_mfma_f32_16x16x32_bf16 v[104:107], v[178:181], v[222:225], v[104:107]
	v_mfma_f32_16x16x32_bf16 v[100:103], v[186:189], v[222:225], v[100:103]
	v_mfma_f32_16x16x32_bf16 v[88:91], v[178:181], v[230:233], v[88:91]
	v_mfma_f32_16x16x32_bf16 v[84:87], v[186:189], v[230:233], v[84:87]
	v_mfma_f32_16x16x32_bf16 v[72:75], v[178:181], v[238:241], v[72:75]
	v_mfma_f32_16x16x32_bf16 v[68:71], v[186:189], v[238:241], v[68:71]
	s_barrier
	s_setprio 0
	s_add_i32 s55, s55, s28
	v_lshl_add_u64 v[242:243], s[22:23], 0, v[140:141]
	s_mov_b32 m0, s55
	ds_read_b128 v[190:193], v213 offset:16384
	ds_read_b128 v[214:217], v213 offset:17408
	ds_read_b128 v[218:221], v213 offset:18432
	ds_read_b128 v[222:225], v213 offset:19456
	ds_read_b128 v[226:229], v213 offset:20480
	ds_read_b128 v[230:233], v213 offset:21504
	ds_read_b128 v[234:237], v213 offset:22528
	ds_read_b128 v[238:241], v213 offset:23552
	global_load_lds_dwordx4 v[242:243], off
	s_add_i32 m0, s55, 0x2000
	s_add_u32 s74, s22, 0x80000
	v_lshl_add_u64 v[244:245], s[22:23], 0, v[136:137]
	s_addc_u32 s75, s23, 0
	s_add_i32 s55, s76, s28
	global_load_lds_dwordx4 v[244:245], off
	v_lshl_add_u64 v[246:247], s[74:75], 0, v[140:141]
	s_mov_b32 m0, s55
	v_lshl_add_u64 v[248:249], s[24:25], 0, v[138:139]
	global_load_lds_dwordx4 v[246:247], off
	v_lshl_add_u64 v[246:247], s[74:75], 0, v[136:137]
	s_add_i32 m0, s55, 0x2000
	s_nop 0
	global_load_lds_dwordx4 v[246:247], off
	v_lshl_add_u64 v[246:247], s[24:25], 0, v[156:157]
	s_mov_b32 m0, s29
	s_nop 0
	global_load_lds_dwordx4 v[246:247], off
	s_mov_b32 m0, s30
	s_nop 0
	global_load_lds_dwordx4 v[248:249], off
	s_waitcnt vmcnt(8)
	s_waitcnt lgkmcnt(0)
	s_setprio 1
	s_barrier
; #define PG8_STAGE(bufoff, gbase, voff) do { _Pragma("unroll") for (int _i = 0; _i < 2; ++_i) \
;         __builtin_amdgcn_global_load_lds((const unsigned*)((const char*)(gbase) + (voff)[_i]), (LAS unsigned*)(lds + (bufoff) + ldsw + _i * 8192), 16, 0, 0); } while (0)
; #define PG8_LDA(dst, b, h) do { _Pragma("unroll") for (int m = 0; m < 4; ++m) _Pragma("unroll") for (int k = 0; k < 2; ++k) dst[m][k] = *(const LAS bf16x8*)(lds + PG8_SA(b, h) + aoff + m * 2048 + k * 1024); } while (0)
; #define PG8_LDB(dst, b, h) do { _Pragma("unroll") for (int n = 0; n < 2; ++n) _Pragma("unroll") for (int k = 0; k < 2; ++k) dst[n][k] = *(const LAS bf16x8*)(lds + PG8_SB(b, h) + boff + n * 2048 + k * 1024); } while (0)
; #define PG8_MMA(ai, bj, At, Bt) do { __builtin_amdgcn_s_setprio(1); _Pragma("unroll") for (int m = 0; m < 4; ++m) _Pragma("unroll") for (int n = 0; n < 2; ++n) _Pragma("unroll") for (int k = 0; k < 2; ++k) \
;         acc[ai][bj][m][n] = __builtin_amdgcn_mfma_f32_16x16x32_bf16(Bt[n][k], At[m][k], acc[ai][bj][m][n], 0, 0, 0); __builtin_amdgcn_s_setprio(0); } while (0)
; #define PG8_WAIT_V(n) asm volatile("s_waitcnt vmcnt(" #n ")" ::: "memory")
; #define PG8_WAIT_L(n) asm volatile("s_waitcnt lgkmcnt(" #n ")" ::: "memory")
; #define PG8_BAR __builtin_amdgcn_s_barrier()
; #define PG8_SCHED __builtin_amdgcn_sched_barrier(0)
; template <class Epi>
; __device__ __forceinline__ void gemm_phase(LAS unsigned char* lds, const Gemm g, const StaticOrder& S, const Epi& E) {
;     ...
;             PG8_WAIT_V(8); PG8_WAIT_L(0); PG8_BAR; PG8_MMA(1, 0, At, B0); PG8_MMA(1, 1, At, B1); PG8_BAR; PG8_SCHED;
;             PG8_LDB(B0, 1, 0); PG8_LDB(B1, 1, 1); PG8_SCHED; PG8_LDA(At, 1, 0); PG8_STAGE(PG8_SA(0, 1), a2 + hstep, voffA);
;             PG8_WAIT_V(8); PG8_WAIT_L(0); PG8_BAR; PG8_MMA(0, 0, At, B0); PG8_MMA(0, 1, At, B1); PG8_BAR; PG8_SCHED;
	v_mfma_f32_16x16x32_bf16 v[64:67], v[132:135], v[190:193], v[64:67]
	v_mfma_f32_16x16x32_bf16 v[60:63], v[166:169], v[190:193], v[60:63]
	v_mfma_f32_16x16x32_bf16 v[48:51], v[132:135], v[218:221], v[48:51]
	v_mfma_f32_16x16x32_bf16 v[44:47], v[166:169], v[218:221], v[44:47]
	v_mfma_f32_16x16x32_bf16 v[32:35], v[132:135], v[226:229], v[32:35]
	v_mfma_f32_16x16x32_bf16 v[28:31], v[166:169], v[226:229], v[28:31]
	v_mfma_f32_16x16x32_bf16 v[16:19], v[132:135], v[234:237], v[16:19]
	v_mfma_f32_16x16x32_bf16 v[12:15], v[166:169], v[234:237], v[12:15]
	v_mfma_f32_16x16x32_bf16 v[64:67], v[162:165], v[214:217], v[64:67]
	v_mfma_f32_16x16x32_bf16 v[60:63], v[170:173], v[214:217], v[60:63]
	v_mfma_f32_16x16x32_bf16 v[48:51], v[162:165], v[222:225], v[48:51]
	v_mfma_f32_16x16x32_bf16 v[44:47], v[170:173], v[222:225], v[44:47]
	v_mfma_f32_16x16x32_bf16 v[32:35], v[162:165], v[230:233], v[32:35]
	v_mfma_f32_16x16x32_bf16 v[28:31], v[170:173], v[230:233], v[28:31]
	v_mfma_f32_16x16x32_bf16 v[16:19], v[162:165], v[238:241], v[16:19]
	v_mfma_f32_16x16x32_bf16 v[12:15], v[170:173], v[238:241], v[12:15]
	s_setprio 0
	s_setprio 1
	v_mfma_f32_16x16x32_bf16 v[56:59], v[174:177], v[190:193], v[56:59]
	v_mfma_f32_16x16x32_bf16 v[52:55], v[182:185], v[190:193], v[52:55]
	v_mfma_f32_16x16x32_bf16 v[40:43], v[174:177], v[218:221], v[40:43]
	v_mfma_f32_16x16x32_bf16 v[36:39], v[182:185], v[218:221], v[36:39]
	v_mfma_f32_16x16x32_bf16 v[24:27], v[174:177], v[226:229], v[24:27]
	v_mfma_f32_16x16x32_bf16 v[20:23], v[182:185], v[226:229], v[20:23]
	v_mfma_f32_16x16x32_bf16 v[8:11], v[174:177], v[234:237], v[8:11]
	v_mfma_f32_16x16x32_bf16 v[4:7], v[182:185], v[234:237], v[4:7]
	v_mfma_f32_16x16x32_bf16 v[56:59], v[178:181], v[214:217], v[56:59]
	v_mfma_f32_16x16x32_bf16 v[52:55], v[186:189], v[214:217], v[52:55]
	v_mfma_f32_16x16x32_bf16 v[40:43], v[178:181], v[222:225], v[40:43]
	v_mfma_f32_16x16x32_bf16 v[36:39], v[186:189], v[222:225], v[36:39]
	v_mfma_f32_16x16x32_bf16 v[24:27], v[178:181], v[230:233], v[24:27]
	v_mfma_f32_16x16x32_bf16 v[20:23], v[186:189], v[230:233], v[20:23]
	v_mfma_f32_16x16x32_bf16 v[8:11], v[178:181], v[238:241], v[8:11]
	v_mfma_f32_16x16x32_bf16 v[4:7], v[186:189], v[238:241], v[4:7]
	s_barrier
	s_setprio 0
	s_add_i32 s55, 0, 0x18000
	s_add_i32 s74, 0, 0x1c000
	v_add_u32_e32 v170, s55, v147
	v_add_u32_e32 v186, s74, v147
	ds_read_b128 v[132:135], v170
	ds_read_b128 v[162:165], v170 offset:1024
	ds_read_b128 v[166:169], v170 offset:2048
	ds_read_b128 v[170:173], v170 offset:3072
	ds_read_b128 v[174:177], v186
	ds_read_b128 v[178:181], v186 offset:1024
	ds_read_b128 v[182:185], v186 offset:2048
	ds_read_b128 v[186:189], v186 offset:3072
	s_add_u32 s24, s24, 0x80000
	s_addc_u32 s25, s25, 0
	s_mov_b32 m0, s31
	v_lshl_add_u64 v[250:251], s[24:25], 0, v[156:157]
	ds_read_b128 v[190:193], v213 offset:32768
	ds_read_b128 v[214:217], v213 offset:33792
	ds_read_b128 v[218:221], v213 offset:34816
	ds_read_b128 v[222:225], v213 offset:35840
	ds_read_b128 v[226:229], v213 offset:36864
	ds_read_b128 v[230:233], v213 offset:37888
	ds_read_b128 v[234:237], v213 offset:38912
	ds_read_b128 v[238:241], v213 offset:39936
	global_load_lds_dwordx4 v[250:251], off
	v_lshl_add_u64 v[250:251], s[24:25], 0, v[138:139]
	s_mov_b32 m0, s34
	s_nop 0
	global_load_lds_dwordx4 v[250:251], off
	s_waitcnt vmcnt(8)
	s_waitcnt lgkmcnt(0)
	s_setprio 1
	s_barrier
	v_mfma_f32_16x16x32_bf16 v[128:131], v[132:135], v[190:193], v[128:131]
	v_mfma_f32_16x16x32_bf16 v[124:127], v[166:169], v[190:193], v[124:127]
	v_mfma_f32_16x16x32_bf16 v[112:115], v[132:135], v[218:221], v[112:115]
	v_mfma_f32_16x16x32_bf16 v[108:111], v[166:169], v[218:221], v[108:111]
	v_mfma_f32_16x16x32_bf16 v[96:99], v[132:135], v[226:229], v[96:99]
	v_mfma_f32_16x16x32_bf16 v[92:95], v[166:169], v[226:229], v[92:95]
	v_mfma_f32_16x16x32_bf16 v[80:83], v[132:135], v[234:237], v[80:83]
	v_mfma_f32_16x16x32_bf16 v[76:79], v[166:169], v[234:237], v[76:79]
	v_mfma_f32_16x16x32_bf16 v[128:131], v[162:165], v[214:217], v[128:131]
	v_mfma_f32_16x16x32_bf16 v[124:127], v[170:173], v[214:217], v[124:127]
	v_mfma_f32_16x16x32_bf16 v[112:115], v[162:165], v[222:225], v[112:115]
	v_mfma_f32_16x16x32_bf16 v[108:111], v[170:173], v[222:225], v[108:111]
	v_mfma_f32_16x16x32_bf16 v[96:99], v[162:165], v[230:233], v[96:99]
	v_mfma_f32_16x16x32_bf16 v[92:95], v[170:173], v[230:233], v[92:95]
	v_mfma_f32_16x16x32_bf16 v[80:83], v[162:165], v[238:241], v[80:83]
	v_mfma_f32_16x16x32_bf16 v[76:79], v[170:173], v[238:241], v[76:79]
	s_setprio 0
	s_setprio 1
	v_mfma_f32_16x16x32_bf16 v[120:123], v[174:177], v[190:193], v[120:123]
	v_mfma_f32_16x16x32_bf16 v[116:119], v[182:185], v[190:193], v[116:119]
	v_mfma_f32_16x16x32_bf16 v[104:107], v[174:177], v[218:221], v[104:107]
	v_mfma_f32_16x16x32_bf16 v[100:103], v[182:185], v[218:221], v[100:103]
	v_mfma_f32_16x16x32_bf16 v[88:91], v[174:177], v[226:229], v[88:91]
	v_mfma_f32_16x16x32_bf16 v[84:87], v[182:185], v[226:229], v[84:87]
	v_mfma_f32_16x16x32_bf16 v[72:75], v[174:177], v[234:237], v[72:75]
	v_mfma_f32_16x16x32_bf16 v[68:71], v[182:185], v[234:237], v[68:71]
	v_mfma_f32_16x16x32_bf16 v[120:123], v[178:181], v[214:217], v[120:123]
	v_mfma_f32_16x16x32_bf16 v[116:119], v[186:189], v[214:217], v[116:119]
	v_mfma_f32_16x16x32_bf16 v[104:107], v[178:181], v[222:225], v[104:107]
	v_mfma_f32_16x16x32_bf16 v[100:103], v[186:189], v[222:225], v[100:103]
	v_mfma_f32_16x16x32_bf16 v[88:91], v[178:181], v[230:233], v[88:91]
	v_mfma_f32_16x16x32_bf16 v[84:87], v[186:189], v[230:233], v[84:87]
	v_mfma_f32_16x16x32_bf16 v[72:75], v[178:181], v[238:241], v[72:75]
	v_mfma_f32_16x16x32_bf16 v[68:71], v[186:189], v[238:241], v[68:71]
	s_barrier
; #define PG8_STAGE(bufoff, gbase, voff) do { _Pragma("unroll") for (int _i = 0; _i < 2; ++_i) \
;         __builtin_amdgcn_global_load_lds((const unsigned*)((const char*)(gbase) + (voff)[_i]), (LAS unsigned*)(lds + (bufoff) + ldsw + _i * 8192), 16, 0, 0); } while (0)
; #define PG8_LDA(dst, b, h) do { _Pragma("unroll") for (int m = 0; m < 4; ++m) _Pragma("unroll") for (int k = 0; k < 2; ++k) dst[m][k] = *(const LAS bf16x8*)(lds + PG8_SA(b, h) + aoff + m * 2048 + k * 1024); } while (0)
; #define PG8_MMA(ai, bj, At, Bt) do { __builtin_amdgcn_s_setprio(1); _Pragma("unroll") for (int m = 0; m < 4; ++m) _Pragma("unroll") for (int n = 0; n < 2; ++n) _Pragma("unroll") for (int k = 0; k < 2; ++k) \
;         acc[ai][bj][m][n] = __builtin_amdgcn_mfma_f32_16x16x32_bf16(Bt[n][k], At[m][k], acc[ai][bj][m][n], 0, 0, 0); __builtin_amdgcn_s_setprio(0); } while (0)
; #define PG8_WAIT_V(n) asm volatile("s_waitcnt vmcnt(" #n ")" ::: "memory")
; #define PG8_WAIT_L(n) asm volatile("s_waitcnt lgkmcnt(" #n ")" ::: "memory")
; #define PG8_BAR __builtin_amdgcn_s_barrier()
; #define PG8_SCHED __builtin_amdgcn_sched_barrier(0)
; template <class Epi>
; __device__ __forceinline__ void gemm_phase(LAS unsigned char* lds, const Gemm g, const StaticOrder& S, const Epi& E) {
;     ...
;             PG8_LDA(At, 1, 1); PG8_STAGE(PG8_SB(1, 0), b3, voffB); PG8_STAGE(PG8_SB(1, 1), b3 + hstep, voffB); PG8_STAGE(PG8_SA(1, 0), a3, voffA);
;             PG8_WAIT_V(8); PG8_WAIT_L(0); PG8_BAR; PG8_MMA(1, 0, At, B0); PG8_MMA(1, 1, At, B1); PG8_BAR; PG8_SCHED;
;         }
	s_setprio 0
	s_add_i32 s24, s55, s28
	v_lshl_add_u64 v[242:243], v[242:243], 0, s[68:69]
	s_mov_b32 m0, s24
	ds_read_b128 v[190:193], v213 offset:49152
	ds_read_b128 v[214:217], v213 offset:50176
	ds_read_b128 v[218:221], v213 offset:51200
	ds_read_b128 v[222:225], v213 offset:52224
	ds_read_b128 v[226:229], v213 offset:53248
	ds_read_b128 v[230:233], v213 offset:54272
	ds_read_b128 v[234:237], v213 offset:55296
	ds_read_b128 v[238:241], v213 offset:56320
	global_load_lds_dwordx4 v[242:243], off
	s_add_i32 m0, s24, 0x2000
	s_add_u32 s22, s22, 0x80080
	v_lshl_add_u64 v[242:243], v[244:245], 0, s[68:69]
	s_addc_u32 s23, s23, 0
	s_add_i32 s24, s74, s28
	global_load_lds_dwordx4 v[242:243], off
	v_lshl_add_u64 v[242:243], s[22:23], 0, v[140:141]
	s_mov_b32 m0, s24
	s_nop 0
	global_load_lds_dwordx4 v[242:243], off
	v_lshl_add_u64 v[242:243], s[22:23], 0, v[136:137]
	s_add_i32 m0, s24, 0x2000
	s_nop 0
	global_load_lds_dwordx4 v[242:243], off
	v_lshl_add_u64 v[242:243], v[246:247], 0, s[68:69]
	s_mov_b32 m0, s35
	s_nop 0
	global_load_lds_dwordx4 v[242:243], off
	v_lshl_add_u64 v[242:243], v[248:249], 0, s[68:69]
	s_mov_b32 m0, s36
	s_nop 0
	global_load_lds_dwordx4 v[242:243], off
	s_waitcnt vmcnt(8)
	s_waitcnt lgkmcnt(0)
	s_setprio 1
	s_barrier
	v_mfma_f32_16x16x32_bf16 v[64:67], v[132:135], v[190:193], v[64:67]
	v_mfma_f32_16x16x32_bf16 v[60:63], v[166:169], v[190:193], v[60:63]
	v_mfma_f32_16x16x32_bf16 v[48:51], v[132:135], v[218:221], v[48:51]
	v_mfma_f32_16x16x32_bf16 v[44:47], v[166:169], v[218:221], v[44:47]
	v_mfma_f32_16x16x32_bf16 v[32:35], v[132:135], v[226:229], v[32:35]
	v_mfma_f32_16x16x32_bf16 v[28:31], v[166:169], v[226:229], v[28:31]
	v_mfma_f32_16x16x32_bf16 v[16:19], v[132:135], v[234:237], v[16:19]
	v_mfma_f32_16x16x32_bf16 v[12:15], v[166:169], v[234:237], v[12:15]
	v_mfma_f32_16x16x32_bf16 v[64:67], v[162:165], v[214:217], v[64:67]
	v_mfma_f32_16x16x32_bf16 v[60:63], v[170:173], v[214:217], v[60:63]
	v_mfma_f32_16x16x32_bf16 v[48:51], v[162:165], v[222:225], v[48:51]
	v_mfma_f32_16x16x32_bf16 v[44:47], v[170:173], v[222:225], v[44:47]
	v_mfma_f32_16x16x32_bf16 v[32:35], v[162:165], v[230:233], v[32:35]
	v_mfma_f32_16x16x32_bf16 v[28:31], v[170:173], v[230:233], v[28:31]
	v_mfma_f32_16x16x32_bf16 v[16:19], v[162:165], v[238:241], v[16:19]
	v_mfma_f32_16x16x32_bf16 v[12:15], v[170:173], v[238:241], v[12:15]
	s_setprio 0
	s_setprio 1
	v_mfma_f32_16x16x32_bf16 v[56:59], v[174:177], v[190:193], v[56:59]
	v_mfma_f32_16x16x32_bf16 v[52:55], v[182:185], v[190:193], v[52:55]
	v_mfma_f32_16x16x32_bf16 v[40:43], v[174:177], v[218:221], v[40:43]
	v_mfma_f32_16x16x32_bf16 v[36:39], v[182:185], v[218:221], v[36:39]
	v_mfma_f32_16x16x32_bf16 v[24:27], v[174:177], v[226:229], v[24:27]
	v_mfma_f32_16x16x32_bf16 v[20:23], v[182:185], v[226:229], v[20:23]
	v_mfma_f32_16x16x32_bf16 v[8:11], v[174:177], v[234:237], v[8:11]
	v_mfma_f32_16x16x32_bf16 v[4:7], v[182:185], v[234:237], v[4:7]
	v_mfma_f32_16x16x32_bf16 v[56:59], v[178:181], v[214:217], v[56:59]
	v_mfma_f32_16x16x32_bf16 v[52:55], v[186:189], v[214:217], v[52:55]
	v_mfma_f32_16x16x32_bf16 v[40:43], v[178:181], v[222:225], v[40:43]
	v_mfma_f32_16x16x32_bf16 v[36:39], v[186:189], v[222:225], v[36:39]
	v_mfma_f32_16x16x32_bf16 v[24:27], v[178:181], v[230:233], v[24:27]
	v_mfma_f32_16x16x32_bf16 v[20:23], v[186:189], v[230:233], v[20:23]
	v_mfma_f32_16x16x32_bf16 v[8:11], v[178:181], v[238:241], v[8:11]
	v_mfma_f32_16x16x32_bf16 v[4:7], v[186:189], v[238:241], v[4:7]
	s_barrier
	s_setprio 0
	s_add_i32 s45, s45, 2
	s_add_u32 s20, s20, 0x100
	s_addc_u32 s21, s21, 0
	s_add_u32 s41, s41, 0x100
	s_addc_u32 s44, s44, 0
	s_cmp_gt_u32 s45, 29
	s_cbranch_scc0 .LBB0_191
	s_and_b64 vcc, exec, s[10:11]
	s_cbranch_vccz .LBB0_194
	s_barrier

; #define PG8_STAGE(bufoff, gbase, voff) do { _Pragma("unroll") for (int _i = 0; _i < 2; ++_i) \
;         __builtin_amdgcn_global_load_lds((const unsigned*)((const char*)(gbase) + (voff)[_i]), (LAS unsigned*)(lds + (bufoff) + ldsw + _i * 8192), 16, 0, 0); } while (0)
; #define PG8_LDA(dst, b, h) do { _Pragma("unroll") for (int m = 0; m < 4; ++m) _Pragma("unroll") for (int k = 0; k < 2; ++k) dst[m][k] = *(const LAS bf16x8*)(lds + PG8_SA(b, h) + aoff + m * 2048 + k * 1024); } while (0)
; #define PG8_LDB(dst, b, h) do { _Pragma("unroll") for (int n = 0; n < 2; ++n) _Pragma("unroll") for (int k = 0; k < 2; ++k) dst[n][k] = *(const LAS bf16x8*)(lds + PG8_SB(b, h) + boff + n * 2048 + k * 1024); } while (0)
; #define PG8_MMA(ai, bj, At, Bt) do { __builtin_amdgcn_s_setprio(1); _Pragma("unroll") for (int m = 0; m < 4; ++m) _Pragma("unroll") for (int n = 0; n < 2; ++n) _Pragma("unroll") for (int k = 0; k < 2; ++k) \
;         acc[ai][bj][m][n] = __builtin_amdgcn_mfma_f32_16x16x32_bf16(Bt[n][k], At[m][k], acc[ai][bj][m][n], 0, 0, 0); __builtin_amdgcn_s_setprio(0); } while (0)
; #define PG8_WAIT_V(n) asm volatile("s_waitcnt vmcnt(" #n ")" ::: "memory")
; #define PG8_WAIT_L(n) asm volatile("s_waitcnt lgkmcnt(" #n ")" ::: "memory")
; #define PG8_BAR __builtin_amdgcn_s_barrier()
; #define PG8_SCHED __builtin_amdgcn_sched_barrier(0)
; template <class Epi>
; __device__ __forceinline__ void gemm_phase(LAS unsigned char* lds, const Gemm g, const StaticOrder& S, const Epi& E) {
;     ...
;             PG8_LDB(B0, 0, 0); PG8_LDB(B1, 0, 1); PG8_SCHED; PG8_LDA(At, 0, 0); PG8_STAGE(PG8_SA(1, 1), a1 + hstep, voffA);
;             PG8_WAIT_V(8); PG8_WAIT_L(0); PG8_BAR; PG8_MMA(0, 0, At, B0); PG8_MMA(0, 1, At, B1); PG8_BAR; PG8_SCHED;
;             PG8_LDA(At, 0, 1); PG8_STAGE(PG8_SB(0, 0), b2, voffB); PG8_STAGE(PG8_SB(0, 1), b2 + hstep, voffB); PG8_STAGE(PG8_SA(0, 0), a2, voffA);
;             PG8_WAIT_V(8); PG8_WAIT_L(0); PG8_BAR; PG8_MMA(1, 0, At, B0); PG8_MMA(1, 1, At, B1); PG8_BAR; PG8_SCHED;
.LBB0_1591:
	s_add_u32 s14, s12, 0xfffc0080
	s_addc_u32 s15, s13, -1
	s_add_i32 s78, 0, 0x10000
	s_cmp_eq_u32 s88, 12
	s_cselect_b32 s29, s23, s15
	s_cselect_b32 s28, s75, s14
	v_add_u32_e32 v3, s78, v176
	s_cselect_b32 s15, s21, s80
	s_cselect_b32 s14, s76, s77
	s_add_i32 s89, 0, 0x14000
	ds_read_b128 v[134:137], v3
	ds_read_b128 v[138:141], v3 offset:1024
	ds_read_b128 v[168:171], v3 offset:2048
	ds_read_b128 v[172:175], v3 offset:3072
	v_add_u32_e32 v3, s89, v176
	ds_read_b128 v[180:183], v3
	ds_read_b128 v[184:187], v3 offset:1024
	ds_read_b128 v[188:191], v3 offset:2048
	ds_read_b128 v[212:215], v3 offset:3072
	v_lshl_add_u64 v[4:5], s[12:13], 0, v[164:165]
	s_add_i32 m0, s37, 0xc000
	ds_read_b128 v[216:219], v178
	ds_read_b128 v[220:223], v178 offset:1024
	ds_read_b128 v[224:227], v178 offset:2048
	ds_read_b128 v[228:231], v178 offset:3072
	ds_read_b128 v[232:235], v178 offset:4096
	ds_read_b128 v[236:239], v178 offset:5120
	ds_read_b128 v[240:243], v178 offset:6144
	ds_read_b128 v[244:247], v178 offset:7168
	global_load_lds_dwordx4 v[4:5], off
	v_lshl_add_u64 v[4:5], s[12:13], 0, v[166:167]
	s_add_i32 m0, s37, 0xe000
	s_nop 0
	global_load_lds_dwordx4 v[4:5], off
	s_waitcnt vmcnt(8)
	s_waitcnt lgkmcnt(0)
	s_setprio 1
	s_barrier
	v_mfma_f32_16x16x32_bf16 v[130:133], v[134:137], v[216:219], v[130:133]
	v_mfma_f32_16x16x32_bf16 v[126:129], v[168:171], v[216:219], v[126:129]
	v_mfma_f32_16x16x32_bf16 v[122:125], v[134:137], v[224:227], v[122:125]
	v_mfma_f32_16x16x32_bf16 v[118:121], v[168:171], v[224:227], v[118:121]
	v_mfma_f32_16x16x32_bf16 v[114:117], v[134:137], v[232:235], v[114:117]
	v_mfma_f32_16x16x32_bf16 v[110:113], v[168:171], v[232:235], v[110:113]
	v_mfma_f32_16x16x32_bf16 v[106:109], v[134:137], v[240:243], v[106:109]
	v_mfma_f32_16x16x32_bf16 v[102:105], v[168:171], v[240:243], v[102:105]
	v_mfma_f32_16x16x32_bf16 v[130:133], v[138:141], v[220:223], v[130:133]
	v_mfma_f32_16x16x32_bf16 v[126:129], v[172:175], v[220:223], v[126:129]
	v_mfma_f32_16x16x32_bf16 v[122:125], v[138:141], v[228:231], v[122:125]
	v_mfma_f32_16x16x32_bf16 v[118:121], v[172:175], v[228:231], v[118:121]
	v_mfma_f32_16x16x32_bf16 v[114:117], v[138:141], v[236:239], v[114:117]
	v_mfma_f32_16x16x32_bf16 v[110:113], v[172:175], v[236:239], v[110:113]
	v_mfma_f32_16x16x32_bf16 v[106:109], v[138:141], v[244:247], v[106:109]
	v_mfma_f32_16x16x32_bf16 v[102:105], v[172:175], v[244:247], v[102:105]
	s_setprio 0
	s_setprio 1
	v_mfma_f32_16x16x32_bf16 v[98:101], v[180:183], v[216:219], v[98:101]
	v_mfma_f32_16x16x32_bf16 v[94:97], v[188:191], v[216:219], v[94:97]
	v_mfma_f32_16x16x32_bf16 v[90:93], v[180:183], v[224:227], v[90:93]
	v_mfma_f32_16x16x32_bf16 v[86:89], v[188:191], v[224:227], v[86:89]
	v_mfma_f32_16x16x32_bf16 v[82:85], v[180:183], v[232:235], v[82:85]
	v_mfma_f32_16x16x32_bf16 v[78:81], v[188:191], v[232:235], v[78:81]
	v_mfma_f32_16x16x32_bf16 v[74:77], v[180:183], v[240:243], v[74:77]
	v_mfma_f32_16x16x32_bf16 v[70:73], v[188:191], v[240:243], v[70:73]
	v_mfma_f32_16x16x32_bf16 v[98:101], v[184:187], v[220:223], v[98:101]
	v_mfma_f32_16x16x32_bf16 v[94:97], v[212:215], v[220:223], v[94:97]
	v_mfma_f32_16x16x32_bf16 v[90:93], v[184:187], v[228:231], v[90:93]
	v_mfma_f32_16x16x32_bf16 v[86:89], v[212:215], v[228:231], v[86:89]
	v_mfma_f32_16x16x32_bf16 v[82:85], v[184:187], v[236:239], v[82:85]
	v_mfma_f32_16x16x32_bf16 v[78:81], v[212:215], v[236:239], v[78:81]
	v_mfma_f32_16x16x32_bf16 v[74:77], v[184:187], v[244:247], v[74:77]
	v_mfma_f32_16x16x32_bf16 v[70:73], v[212:215], v[244:247], v[70:73]
	s_barrier
	s_setprio 0
	s_add_i32 s78, s78, s34
	v_lshl_add_u64 v[192:193], s[14:15], 0, v[160:161]
	s_mov_b32 m0, s78
	ds_read_b128 v[216:219], v178 offset:16384
	ds_read_b128 v[220:223], v178 offset:17408
	ds_read_b128 v[224:227], v178 offset:18432
	ds_read_b128 v[228:231], v178 offset:19456
	ds_read_b128 v[232:235], v178 offset:20480
	ds_read_b128 v[236:239], v178 offset:21504
	ds_read_b128 v[240:243], v178 offset:22528
	ds_read_b128 v[244:247], v178 offset:23552
	global_load_lds_dwordx4 v[192:193], off
	s_add_i32 m0, s78, 0x2000
	s_add_u32 s78, s14, 0x40000
	v_lshl_add_u64 v[248:249], s[14:15], 0, v[156:157]
	s_addc_u32 s79, s15, 0
	s_add_i32 s89, s89, s34
	global_load_lds_dwordx4 v[248:249], off
	v_lshl_add_u64 v[4:5], s[78:79], 0, v[160:161]
	s_mov_b32 m0, s89
	v_lshl_add_u64 v[250:251], s[28:29], 0, v[162:163]
	global_load_lds_dwordx4 v[4:5], off
	v_lshl_add_u64 v[4:5], s[78:79], 0, v[156:157]
	s_add_i32 m0, s89, 0x2000
	v_lshl_add_u64 v[198:199], s[28:29], 0, v[158:159]
	global_load_lds_dwordx4 v[4:5], off
	s_mov_b32 m0, s37
	s_nop 0
	global_load_lds_dwordx4 v[250:251], off
	s_mov_b32 m0, s38
	s_nop 0
	global_load_lds_dwordx4 v[198:199], off
	s_waitcnt vmcnt(8)
	s_waitcnt lgkmcnt(0)
	s_setprio 1
	s_barrier
; #define PG8_STAGE(bufoff, gbase, voff) do { _Pragma("unroll") for (int _i = 0; _i < 2; ++_i) \
;         __builtin_amdgcn_global_load_lds((const unsigned*)((const char*)(gbase) + (voff)[_i]), (LAS unsigned*)(lds + (bufoff) + ldsw + _i * 8192), 16, 0, 0); } while (0)
; #define PG8_LDA(dst, b, h) do { _Pragma("unroll") for (int m = 0; m < 4; ++m) _Pragma("unroll") for (int k = 0; k < 2; ++k) dst[m][k] = *(const LAS bf16x8*)(lds + PG8_SA(b, h) + aoff + m * 2048 + k * 1024); } while (0)
; #define PG8_LDB(dst, b, h) do { _Pragma("unroll") for (int n = 0; n < 2; ++n) _Pragma("unroll") for (int k = 0; k < 2; ++k) dst[n][k] = *(const LAS bf16x8*)(lds + PG8_SB(b, h) + boff + n * 2048 + k * 1024); } while (0)
; #define PG8_MMA(ai, bj, At, Bt) do { __builtin_amdgcn_s_setprio(1); _Pragma("unroll") for (int m = 0; m < 4; ++m) _Pragma("unroll") for (int n = 0; n < 2; ++n) _Pragma("unroll") for (int k = 0; k < 2; ++k) \
;         acc[ai][bj][m][n] = __builtin_amdgcn_mfma_f32_16x16x32_bf16(Bt[n][k], At[m][k], acc[ai][bj][m][n], 0, 0, 0); __builtin_amdgcn_s_setprio(0); } while (0)
; #define PG8_WAIT_V(n) asm volatile("s_waitcnt vmcnt(" #n ")" ::: "memory")
; #define PG8_WAIT_L(n) asm volatile("s_waitcnt lgkmcnt(" #n ")" ::: "memory")
; #define PG8_BAR __builtin_amdgcn_s_barrier()
; #define PG8_SCHED __builtin_amdgcn_sched_barrier(0)
; template <class Epi>
; __device__ __forceinline__ void gemm_phase(LAS unsigned char* lds, const Gemm g, const StaticOrder& S, const Epi& E) {
;     ...
;             PG8_WAIT_V(8); PG8_WAIT_L(0); PG8_BAR; PG8_MMA(1, 0, At, B0); PG8_MMA(1, 1, At, B1); PG8_BAR; PG8_SCHED;
;             PG8_LDB(B0, 1, 0); PG8_LDB(B1, 1, 1); PG8_SCHED; PG8_LDA(At, 1, 0); PG8_STAGE(PG8_SA(0, 1), a2 + hstep, voffA);
;             PG8_WAIT_V(8); PG8_WAIT_L(0); PG8_BAR; PG8_MMA(0, 0, At, B0); PG8_MMA(0, 1, At, B1); PG8_BAR; PG8_SCHED;
	v_mfma_f32_16x16x32_bf16 v[66:69], v[134:137], v[216:219], v[66:69]
	v_mfma_f32_16x16x32_bf16 v[62:65], v[168:171], v[216:219], v[62:65]
	v_mfma_f32_16x16x32_bf16 v[58:61], v[134:137], v[224:227], v[58:61]
	v_mfma_f32_16x16x32_bf16 v[54:57], v[168:171], v[224:227], v[54:57]
	v_mfma_f32_16x16x32_bf16 v[50:53], v[134:137], v[232:235], v[50:53]
	v_mfma_f32_16x16x32_bf16 v[46:49], v[168:171], v[232:235], v[46:49]
	v_mfma_f32_16x16x32_bf16 v[42:45], v[134:137], v[240:243], v[42:45]
	v_mfma_f32_16x16x32_bf16 v[38:41], v[168:171], v[240:243], v[38:41]
	v_mfma_f32_16x16x32_bf16 v[66:69], v[138:141], v[220:223], v[66:69]
	v_mfma_f32_16x16x32_bf16 v[62:65], v[172:175], v[220:223], v[62:65]
	v_mfma_f32_16x16x32_bf16 v[58:61], v[138:141], v[228:231], v[58:61]
	v_mfma_f32_16x16x32_bf16 v[54:57], v[172:175], v[228:231], v[54:57]
	v_mfma_f32_16x16x32_bf16 v[50:53], v[138:141], v[236:239], v[50:53]
	v_mfma_f32_16x16x32_bf16 v[46:49], v[172:175], v[236:239], v[46:49]
	v_mfma_f32_16x16x32_bf16 v[42:45], v[138:141], v[244:247], v[42:45]
	v_mfma_f32_16x16x32_bf16 v[38:41], v[172:175], v[244:247], v[38:41]
	s_setprio 0
	s_setprio 1
	v_mfma_f32_16x16x32_bf16 v[34:37], v[180:183], v[216:219], v[34:37]
	v_mfma_f32_16x16x32_bf16 v[30:33], v[188:191], v[216:219], v[30:33]
	v_mfma_f32_16x16x32_bf16 v[26:29], v[180:183], v[224:227], v[26:29]
	v_mfma_f32_16x16x32_bf16 v[22:25], v[188:191], v[224:227], v[22:25]
	v_mfma_f32_16x16x32_bf16 v[18:21], v[180:183], v[232:235], v[18:21]
	v_mfma_f32_16x16x32_bf16 v[14:17], v[188:191], v[232:235], v[14:17]
	v_mfma_f32_16x16x32_bf16 v[10:13], v[180:183], v[240:243], v[10:13]
	v_mfma_f32_16x16x32_bf16 v[4:7], v[188:191], v[240:243], v[6:9]
	v_mfma_f32_16x16x32_bf16 v[34:37], v[184:187], v[220:223], v[34:37]
	v_mfma_f32_16x16x32_bf16 v[30:33], v[212:215], v[220:223], v[30:33]
	v_mfma_f32_16x16x32_bf16 v[26:29], v[184:187], v[228:231], v[26:29]
	v_mfma_f32_16x16x32_bf16 v[22:25], v[212:215], v[228:231], v[22:25]
	v_mfma_f32_16x16x32_bf16 v[18:21], v[184:187], v[236:239], v[18:21]
	v_mfma_f32_16x16x32_bf16 v[14:17], v[212:215], v[236:239], v[14:17]
	v_mfma_f32_16x16x32_bf16 v[10:13], v[184:187], v[244:247], v[10:13]
	v_mfma_f32_16x16x32_bf16 v[4:7], v[212:215], v[244:247], v[4:7]
	s_barrier
	s_setprio 0
	s_add_i32 s78, 0, 0x18000
	v_add_u32_e32 v3, s78, v176
	s_add_i32 s79, 0, 0x1c000
	ds_read_b128 v[134:137], v3
	ds_read_b128 v[138:141], v3 offset:1024
	ds_read_b128 v[168:171], v3 offset:2048
	ds_read_b128 v[172:175], v3 offset:3072
	v_add_u32_e32 v3, s79, v176
	ds_read_b128 v[180:183], v3
	ds_read_b128 v[184:187], v3 offset:1024
	ds_read_b128 v[188:191], v3 offset:2048
	ds_read_b128 v[212:215], v3 offset:3072
	s_add_u32 s28, s28, 0x40000
	s_addc_u32 s29, s29, 0
	s_mov_b32 m0, s39
	v_lshl_add_u64 v[8:9], s[28:29], 0, v[162:163]
	ds_read_b128 v[216:219], v178 offset:32768
	ds_read_b128 v[220:223], v178 offset:33792
	ds_read_b128 v[224:227], v178 offset:34816
	ds_read_b128 v[228:231], v178 offset:35840
	ds_read_b128 v[232:235], v178 offset:36864
	ds_read_b128 v[236:239], v178 offset:37888
	ds_read_b128 v[240:243], v178 offset:38912
	ds_read_b128 v[244:247], v178 offset:39936
	global_load_lds_dwordx4 v[8:9], off
	v_lshl_add_u64 v[8:9], s[28:29], 0, v[158:159]
	s_mov_b32 m0, s40
	s_nop 0
	global_load_lds_dwordx4 v[8:9], off
	s_waitcnt vmcnt(8)
	s_waitcnt lgkmcnt(0)
	s_setprio 1
	s_barrier
	v_mfma_f32_16x16x32_bf16 v[130:133], v[134:137], v[216:219], v[130:133]
	v_mfma_f32_16x16x32_bf16 v[126:129], v[168:171], v[216:219], v[126:129]
	v_mfma_f32_16x16x32_bf16 v[122:125], v[134:137], v[224:227], v[122:125]
	v_mfma_f32_16x16x32_bf16 v[118:121], v[168:171], v[224:227], v[118:121]
	v_mfma_f32_16x16x32_bf16 v[114:117], v[134:137], v[232:235], v[114:117]
	v_mfma_f32_16x16x32_bf16 v[110:113], v[168:171], v[232:235], v[110:113]
	v_mfma_f32_16x16x32_bf16 v[106:109], v[134:137], v[240:243], v[106:109]
	v_mfma_f32_16x16x32_bf16 v[102:105], v[168:171], v[240:243], v[102:105]
	v_mfma_f32_16x16x32_bf16 v[130:133], v[138:141], v[220:223], v[130:133]
	v_mfma_f32_16x16x32_bf16 v[126:129], v[172:175], v[220:223], v[126:129]
	v_mfma_f32_16x16x32_bf16 v[122:125], v[138:141], v[228:231], v[122:125]
	v_mfma_f32_16x16x32_bf16 v[118:121], v[172:175], v[228:231], v[118:121]
	v_mfma_f32_16x16x32_bf16 v[114:117], v[138:141], v[236:239], v[114:117]
	v_mfma_f32_16x16x32_bf16 v[110:113], v[172:175], v[236:239], v[110:113]
	v_mfma_f32_16x16x32_bf16 v[106:109], v[138:141], v[244:247], v[106:109]
	v_mfma_f32_16x16x32_bf16 v[102:105], v[172:175], v[244:247], v[102:105]
	s_setprio 0
	s_setprio 1
	v_mfma_f32_16x16x32_bf16 v[98:101], v[180:183], v[216:219], v[98:101]
	v_mfma_f32_16x16x32_bf16 v[94:97], v[188:191], v[216:219], v[94:97]
	v_mfma_f32_16x16x32_bf16 v[90:93], v[180:183], v[224:227], v[90:93]
	v_mfma_f32_16x16x32_bf16 v[86:89], v[188:191], v[224:227], v[86:89]
	v_mfma_f32_16x16x32_bf16 v[82:85], v[180:183], v[232:235], v[82:85]
	v_mfma_f32_16x16x32_bf16 v[78:81], v[188:191], v[232:235], v[78:81]
	v_mfma_f32_16x16x32_bf16 v[74:77], v[180:183], v[240:243], v[74:77]
	v_mfma_f32_16x16x32_bf16 v[70:73], v[188:191], v[240:243], v[70:73]
	v_mfma_f32_16x16x32_bf16 v[98:101], v[184:187], v[220:223], v[98:101]
	v_mfma_f32_16x16x32_bf16 v[94:97], v[212:215], v[220:223], v[94:97]
	v_mfma_f32_16x16x32_bf16 v[90:93], v[184:187], v[228:231], v[90:93]
	v_mfma_f32_16x16x32_bf16 v[86:89], v[212:215], v[228:231], v[86:89]
	v_mfma_f32_16x16x32_bf16 v[82:85], v[184:187], v[236:239], v[82:85]
	v_mfma_f32_16x16x32_bf16 v[78:81], v[212:215], v[236:239], v[78:81]
	v_mfma_f32_16x16x32_bf16 v[74:77], v[184:187], v[244:247], v[74:77]
	v_mfma_f32_16x16x32_bf16 v[70:73], v[212:215], v[244:247], v[70:73]
	s_barrier
; #define PG8_STAGE(bufoff, gbase, voff) do { _Pragma("unroll") for (int _i = 0; _i < 2; ++_i) \
;         __builtin_amdgcn_global_load_lds((const unsigned*)((const char*)(gbase) + (voff)[_i]), (LAS unsigned*)(lds + (bufoff) + ldsw + _i * 8192), 16, 0, 0); } while (0)
; #define PG8_LDA(dst, b, h) do { _Pragma("unroll") for (int m = 0; m < 4; ++m) _Pragma("unroll") for (int k = 0; k < 2; ++k) dst[m][k] = *(const LAS bf16x8*)(lds + PG8_SA(b, h) + aoff + m * 2048 + k * 1024); } while (0)
; #define PG8_MMA(ai, bj, At, Bt) do { __builtin_amdgcn_s_setprio(1); _Pragma("unroll") for (int m = 0; m < 4; ++m) _Pragma("unroll") for (int n = 0; n < 2; ++n) _Pragma("unroll") for (int k = 0; k < 2; ++k) \
;         acc[ai][bj][m][n] = __builtin_amdgcn_mfma_f32_16x16x32_bf16(Bt[n][k], At[m][k], acc[ai][bj][m][n], 0, 0, 0); __builtin_amdgcn_s_setprio(0); } while (0)
; #define PG8_WAIT_V(n) asm volatile("s_waitcnt vmcnt(" #n ")" ::: "memory")
; #define PG8_WAIT_L(n) asm volatile("s_waitcnt lgkmcnt(" #n ")" ::: "memory")
; #define PG8_BAR __builtin_amdgcn_s_barrier()
; #define PG8_SCHED __builtin_amdgcn_sched_barrier(0)
; template <class Epi>
; __device__ __forceinline__ void gemm_phase(LAS unsigned char* lds, const Gemm g, const StaticOrder& S, const Epi& E) {
;     ...
;             PG8_LDA(At, 1, 1); PG8_STAGE(PG8_SB(1, 0), b3, voffB); PG8_STAGE(PG8_SB(1, 1), b3 + hstep, voffB); PG8_STAGE(PG8_SA(1, 0), a3, voffA);
;             PG8_WAIT_V(8); PG8_WAIT_L(0); PG8_BAR; PG8_MMA(1, 0, At, B0); PG8_MMA(1, 1, At, B1); PG8_BAR; PG8_SCHED;
;         }
	s_setprio 0
	s_add_i32 s28, s78, s34
	v_lshl_add_u64 v[8:9], v[192:193], 0, s[68:69]
	s_mov_b32 m0, s28
	ds_read_b128 v[216:219], v178 offset:49152
	ds_read_b128 v[220:223], v178 offset:50176
	ds_read_b128 v[224:227], v178 offset:51200
	ds_read_b128 v[228:231], v178 offset:52224
	ds_read_b128 v[232:235], v178 offset:53248
	ds_read_b128 v[236:239], v178 offset:54272
	ds_read_b128 v[240:243], v178 offset:55296
	ds_read_b128 v[244:247], v178 offset:56320
	global_load_lds_dwordx4 v[8:9], off
	s_add_i32 m0, s28, 0x2000
	s_add_u32 s14, s14, 0x40080
	v_lshl_add_u64 v[8:9], v[248:249], 0, s[68:69]
	s_addc_u32 s15, s15, 0
	s_add_i32 s28, s79, s34
	global_load_lds_dwordx4 v[8:9], off
	v_lshl_add_u64 v[8:9], s[14:15], 0, v[160:161]
	s_mov_b32 m0, s28
	s_nop 0
	global_load_lds_dwordx4 v[8:9], off
	v_lshl_add_u64 v[8:9], s[14:15], 0, v[156:157]
	s_add_i32 m0, s28, 0x2000
	s_nop 0
	global_load_lds_dwordx4 v[8:9], off
	v_lshl_add_u64 v[8:9], v[250:251], 0, s[68:69]
	s_mov_b32 m0, s41
	s_nop 0
	global_load_lds_dwordx4 v[8:9], off
	v_lshl_add_u64 v[8:9], v[198:199], 0, s[68:69]
	s_mov_b32 m0, s44
	s_nop 0
	global_load_lds_dwordx4 v[8:9], off
	s_waitcnt vmcnt(8)
	s_waitcnt lgkmcnt(0)
	s_setprio 1
	s_barrier
	v_mfma_f32_16x16x32_bf16 v[66:69], v[134:137], v[216:219], v[66:69]
	v_mfma_f32_16x16x32_bf16 v[62:65], v[168:171], v[216:219], v[62:65]
	v_mfma_f32_16x16x32_bf16 v[58:61], v[134:137], v[224:227], v[58:61]
	v_mfma_f32_16x16x32_bf16 v[54:57], v[168:171], v[224:227], v[54:57]
	v_mfma_f32_16x16x32_bf16 v[50:53], v[134:137], v[232:235], v[50:53]
	v_mfma_f32_16x16x32_bf16 v[46:49], v[168:171], v[232:235], v[46:49]
	v_mfma_f32_16x16x32_bf16 v[42:45], v[134:137], v[240:243], v[42:45]
	v_mfma_f32_16x16x32_bf16 v[38:41], v[168:171], v[240:243], v[38:41]
	v_mfma_f32_16x16x32_bf16 v[66:69], v[138:141], v[220:223], v[66:69]
	v_mfma_f32_16x16x32_bf16 v[62:65], v[172:175], v[220:223], v[62:65]
	v_mfma_f32_16x16x32_bf16 v[58:61], v[138:141], v[228:231], v[58:61]
	v_mfma_f32_16x16x32_bf16 v[54:57], v[172:175], v[228:231], v[54:57]
	v_mfma_f32_16x16x32_bf16 v[50:53], v[138:141], v[236:239], v[50:53]
	v_mfma_f32_16x16x32_bf16 v[46:49], v[172:175], v[236:239], v[46:49]
	v_mfma_f32_16x16x32_bf16 v[42:45], v[138:141], v[244:247], v[42:45]
	v_mfma_f32_16x16x32_bf16 v[38:41], v[172:175], v[244:247], v[38:41]
	s_setprio 0
	s_setprio 1
	v_mfma_f32_16x16x32_bf16 v[34:37], v[180:183], v[216:219], v[34:37]
	v_mfma_f32_16x16x32_bf16 v[30:33], v[188:191], v[216:219], v[30:33]
	v_mfma_f32_16x16x32_bf16 v[26:29], v[180:183], v[224:227], v[26:29]
	v_mfma_f32_16x16x32_bf16 v[22:25], v[188:191], v[224:227], v[22:25]
	v_mfma_f32_16x16x32_bf16 v[18:21], v[180:183], v[232:235], v[18:21]
	v_mfma_f32_16x16x32_bf16 v[14:17], v[188:191], v[232:235], v[14:17]
	v_mfma_f32_16x16x32_bf16 v[8:11], v[180:183], v[240:243], v[10:13]
	v_mfma_f32_16x16x32_bf16 v[4:7], v[188:191], v[240:243], v[4:7]
	v_mfma_f32_16x16x32_bf16 v[34:37], v[184:187], v[220:223], v[34:37]
	v_mfma_f32_16x16x32_bf16 v[30:33], v[212:215], v[220:223], v[30:33]
	v_mfma_f32_16x16x32_bf16 v[26:29], v[184:187], v[228:231], v[26:29]
	v_mfma_f32_16x16x32_bf16 v[22:25], v[212:215], v[228:231], v[22:25]
	v_mfma_f32_16x16x32_bf16 v[18:21], v[184:187], v[236:239], v[18:21]
	v_mfma_f32_16x16x32_bf16 v[14:17], v[212:215], v[236:239], v[14:17]
	v_mfma_f32_16x16x32_bf16 v[10:13], v[184:187], v[244:247], v[8:11]
	v_mfma_f32_16x16x32_bf16 v[6:9], v[212:215], v[244:247], v[4:7]
	s_barrier
	s_setprio 0
	s_add_i32 s88, s88, 2
	s_add_u32 s12, s12, 0x100
	s_addc_u32 s13, s13, 0
	s_add_u32 s77, s77, 0x100
	s_addc_u32 s80, s80, 0
	s_cmp_gt_u32 s88, 13
	s_cbranch_scc0 .LBB0_1591
	s_and_b64 vcc, exec, s[18:19]
	s_cbranch_vccz .LBB0_1594
	s_barrier

; #define PG8_STAGE(bufoff, gbase, voff) do { _Pragma("unroll") for (int _i = 0; _i < 2; ++_i) \
;         __builtin_amdgcn_global_load_lds((const unsigned*)((const char*)(gbase) + (voff)[_i]), (LAS unsigned*)(lds + (bufoff) + ldsw + _i * 8192), 16, 0, 0); } while (0)
; #define PG8_LDA(dst, b, h) do { _Pragma("unroll") for (int m = 0; m < 4; ++m) _Pragma("unroll") for (int k = 0; k < 2; ++k) dst[m][k] = *(const LAS bf16x8*)(lds + PG8_SA(b, h) + aoff + m * 2048 + k * 1024); } while (0)
; #define PG8_LDB(dst, b, h) do { _Pragma("unroll") for (int n = 0; n < 2; ++n) _Pragma("unroll") for (int k = 0; k < 2; ++k) dst[n][k] = *(const LAS bf16x8*)(lds + PG8_SB(b, h) + boff + n * 2048 + k * 1024); } while (0)
; #define PG8_MMA(ai, bj, At, Bt) do { __builtin_amdgcn_s_setprio(1); _Pragma("unroll") for (int m = 0; m < 4; ++m) _Pragma("unroll") for (int n = 0; n < 2; ++n) _Pragma("unroll") for (int k = 0; k < 2; ++k) \
;         acc[ai][bj][m][n] = __builtin_amdgcn_mfma_f32_16x16x32_bf16(Bt[n][k], At[m][k], acc[ai][bj][m][n], 0, 0, 0); __builtin_amdgcn_s_setprio(0); } while (0)
; #define PG8_WAIT_V(n) asm volatile("s_waitcnt vmcnt(" #n ")" ::: "memory")
; #define PG8_WAIT_L(n) asm volatile("s_waitcnt lgkmcnt(" #n ")" ::: "memory")
; #define PG8_BAR __builtin_amdgcn_s_barrier()
; #define PG8_SCHED __builtin_amdgcn_sched_barrier(0)
; template <class Epi>
; __device__ __forceinline__ void gemm_phase(LAS unsigned char* lds, const Gemm g, const StaticOrder& S, const Epi& E) {
;     ...
;             PG8_LDB(B0, 0, 0); PG8_LDB(B1, 0, 1); PG8_SCHED; PG8_LDA(At, 0, 0); PG8_STAGE(PG8_SA(1, 1), a1 + hstep, voffA);
;             PG8_WAIT_V(8); PG8_WAIT_L(0); PG8_BAR; PG8_MMA(0, 0, At, B0); PG8_MMA(0, 1, At, B1); PG8_BAR; PG8_SCHED;
;             PG8_LDA(At, 0, 1); PG8_STAGE(PG8_SB(0, 0), b2, voffB); PG8_STAGE(PG8_SB(0, 1), b2 + hstep, voffB); PG8_STAGE(PG8_SA(0, 0), a2, voffA);
;             PG8_WAIT_V(8); PG8_WAIT_L(0); PG8_BAR; PG8_MMA(1, 0, At, B0); PG8_MMA(1, 1, At, B1); PG8_BAR; PG8_SCHED;
.LBB0_1741:
	s_add_u32 s28, s26, 0xfff80080
	s_addc_u32 s29, s27, -1
	s_add_i32 s78, 0, 0x10000
	s_cmp_eq_u32 s80, 28
	s_cselect_b32 s31, s21, s29
	s_cselect_b32 s30, s74, s28
	v_add_u32_e32 v162, s78, v147
	s_cselect_b32 s29, s19, s77
	s_cselect_b32 s28, s75, s76
	s_add_i32 s88, 0, 0x14000
	ds_read_b128 v[158:161], v162
	ds_read_b128 v[166:169], v162 offset:1024
	ds_read_b128 v[170:173], v162 offset:2048
	ds_read_b128 v[174:177], v162 offset:3072
	v_add_u32_e32 v162, s88, v147
	ds_read_b128 v[178:181], v162
	ds_read_b128 v[182:185], v162 offset:1024
	ds_read_b128 v[186:189], v162 offset:2048
	ds_read_b128 v[190:193], v162 offset:3072
	v_lshl_add_u64 v[162:163], s[26:27], 0, v[140:141]
	s_add_i32 m0, s35, 0xc000
	ds_read_b128 v[212:215], v165
	ds_read_b128 v[216:219], v165 offset:1024
	ds_read_b128 v[220:223], v165 offset:2048
	ds_read_b128 v[224:227], v165 offset:3072
	ds_read_b128 v[228:231], v165 offset:4096
	ds_read_b128 v[232:235], v165 offset:5120
	ds_read_b128 v[236:239], v165 offset:6144
	ds_read_b128 v[240:243], v165 offset:7168
	global_load_lds_dwordx4 v[162:163], off
	v_lshl_add_u64 v[162:163], s[26:27], 0, v[156:157]
	s_add_i32 m0, s35, 0xe000
	s_nop 0
	global_load_lds_dwordx4 v[162:163], off
	s_waitcnt vmcnt(8)
	s_waitcnt lgkmcnt(0)
	s_setprio 1
	s_barrier
	v_mfma_f32_16x16x32_bf16 v[128:131], v[158:161], v[212:215], v[128:131]
	v_mfma_f32_16x16x32_bf16 v[124:127], v[170:173], v[212:215], v[124:127]
	v_mfma_f32_16x16x32_bf16 v[112:115], v[158:161], v[220:223], v[112:115]
	v_mfma_f32_16x16x32_bf16 v[108:111], v[170:173], v[220:223], v[108:111]
	v_mfma_f32_16x16x32_bf16 v[96:99], v[158:161], v[228:231], v[96:99]
	v_mfma_f32_16x16x32_bf16 v[92:95], v[170:173], v[228:231], v[92:95]
	v_mfma_f32_16x16x32_bf16 v[80:83], v[158:161], v[236:239], v[80:83]
	v_mfma_f32_16x16x32_bf16 v[76:79], v[170:173], v[236:239], v[76:79]
	v_mfma_f32_16x16x32_bf16 v[128:131], v[166:169], v[216:219], v[128:131]
	v_mfma_f32_16x16x32_bf16 v[124:127], v[174:177], v[216:219], v[124:127]
	v_mfma_f32_16x16x32_bf16 v[112:115], v[166:169], v[224:227], v[112:115]
	v_mfma_f32_16x16x32_bf16 v[108:111], v[174:177], v[224:227], v[108:111]
	v_mfma_f32_16x16x32_bf16 v[96:99], v[166:169], v[232:235], v[96:99]
	v_mfma_f32_16x16x32_bf16 v[92:95], v[174:177], v[232:235], v[92:95]
	v_mfma_f32_16x16x32_bf16 v[80:83], v[166:169], v[240:243], v[80:83]
	v_mfma_f32_16x16x32_bf16 v[76:79], v[174:177], v[240:243], v[76:79]
	s_setprio 0
	s_setprio 1
	v_mfma_f32_16x16x32_bf16 v[120:123], v[178:181], v[212:215], v[120:123]
	v_mfma_f32_16x16x32_bf16 v[116:119], v[186:189], v[212:215], v[116:119]
	v_mfma_f32_16x16x32_bf16 v[104:107], v[178:181], v[220:223], v[104:107]
	v_mfma_f32_16x16x32_bf16 v[100:103], v[186:189], v[220:223], v[100:103]
	v_mfma_f32_16x16x32_bf16 v[88:91], v[178:181], v[228:231], v[88:91]
	v_mfma_f32_16x16x32_bf16 v[84:87], v[186:189], v[228:231], v[84:87]
	v_mfma_f32_16x16x32_bf16 v[72:75], v[178:181], v[236:239], v[72:75]
	v_mfma_f32_16x16x32_bf16 v[68:71], v[186:189], v[236:239], v[68:71]
	v_mfma_f32_16x16x32_bf16 v[120:123], v[182:185], v[216:219], v[120:123]
	v_mfma_f32_16x16x32_bf16 v[116:119], v[190:193], v[216:219], v[116:119]
	v_mfma_f32_16x16x32_bf16 v[104:107], v[182:185], v[224:227], v[104:107]
	v_mfma_f32_16x16x32_bf16 v[100:103], v[190:193], v[224:227], v[100:103]
	v_mfma_f32_16x16x32_bf16 v[88:91], v[182:185], v[232:235], v[88:91]
	v_mfma_f32_16x16x32_bf16 v[84:87], v[190:193], v[232:235], v[84:87]
	v_mfma_f32_16x16x32_bf16 v[72:75], v[182:185], v[240:243], v[72:75]
	v_mfma_f32_16x16x32_bf16 v[68:71], v[190:193], v[240:243], v[68:71]
	s_barrier
	s_setprio 0
	s_add_i32 s78, s78, s34
	v_lshl_add_u64 v[162:163], s[28:29], 0, v[136:137]
	s_mov_b32 m0, s78
	ds_read_b128 v[212:215], v165 offset:16384
	ds_read_b128 v[216:219], v165 offset:17408
	ds_read_b128 v[220:223], v165 offset:18432
	ds_read_b128 v[224:227], v165 offset:19456
	ds_read_b128 v[228:231], v165 offset:20480
	ds_read_b128 v[232:235], v165 offset:21504
	ds_read_b128 v[236:239], v165 offset:22528
	ds_read_b128 v[240:243], v165 offset:23552
	global_load_lds_dwordx4 v[162:163], off
	s_add_i32 m0, s78, 0x2000
	s_add_u32 s78, s28, 0x80000
	v_lshl_add_u64 v[198:199], s[28:29], 0, v[132:133]
	s_addc_u32 s79, s29, 0
	s_add_i32 s88, s88, s34
	global_load_lds_dwordx4 v[198:199], off
	v_lshl_add_u64 v[244:245], s[78:79], 0, v[136:137]
	s_mov_b32 m0, s88
	v_lshl_add_u64 v[246:247], s[30:31], 0, v[134:135]
	global_load_lds_dwordx4 v[244:245], off
	v_lshl_add_u64 v[244:245], s[78:79], 0, v[132:133]
	s_add_i32 m0, s88, 0x2000
	s_nop 0
	global_load_lds_dwordx4 v[244:245], off
	v_lshl_add_u64 v[244:245], s[30:31], 0, v[138:139]
	s_mov_b32 m0, s35
	s_nop 0
	global_load_lds_dwordx4 v[244:245], off
	s_mov_b32 m0, s36
	s_nop 0
	global_load_lds_dwordx4 v[246:247], off
	s_waitcnt vmcnt(8)
	s_waitcnt lgkmcnt(0)
	s_setprio 1
	s_barrier
; #define PG8_STAGE(bufoff, gbase, voff) do { _Pragma("unroll") for (int _i = 0; _i < 2; ++_i) \
;         __builtin_amdgcn_global_load_lds((const unsigned*)((const char*)(gbase) + (voff)[_i]), (LAS unsigned*)(lds + (bufoff) + ldsw + _i * 8192), 16, 0, 0); } while (0)
; #define PG8_LDA(dst, b, h) do { _Pragma("unroll") for (int m = 0; m < 4; ++m) _Pragma("unroll") for (int k = 0; k < 2; ++k) dst[m][k] = *(const LAS bf16x8*)(lds + PG8_SA(b, h) + aoff + m * 2048 + k * 1024); } while (0)
; #define PG8_LDB(dst, b, h) do { _Pragma("unroll") for (int n = 0; n < 2; ++n) _Pragma("unroll") for (int k = 0; k < 2; ++k) dst[n][k] = *(const LAS bf16x8*)(lds + PG8_SB(b, h) + boff + n * 2048 + k * 1024); } while (0)
; #define PG8_MMA(ai, bj, At, Bt) do { __builtin_amdgcn_s_setprio(1); _Pragma("unroll") for (int m = 0; m < 4; ++m) _Pragma("unroll") for (int n = 0; n < 2; ++n) _Pragma("unroll") for (int k = 0; k < 2; ++k) \
;         acc[ai][bj][m][n] = __builtin_amdgcn_mfma_f32_16x16x32_bf16(Bt[n][k], At[m][k], acc[ai][bj][m][n], 0, 0, 0); __builtin_amdgcn_s_setprio(0); } while (0)
; #define PG8_WAIT_V(n) asm volatile("s_waitcnt vmcnt(" #n ")" ::: "memory")
; #define PG8_WAIT_L(n) asm volatile("s_waitcnt lgkmcnt(" #n ")" ::: "memory")
; #define PG8_BAR __builtin_amdgcn_s_barrier()
; #define PG8_SCHED __builtin_amdgcn_sched_barrier(0)
; template <class Epi>
; __device__ __forceinline__ void gemm_phase(LAS unsigned char* lds, const Gemm g, const StaticOrder& S, const Epi& E) {
;     ...
;             PG8_WAIT_V(8); PG8_WAIT_L(0); PG8_BAR; PG8_MMA(1, 0, At, B0); PG8_MMA(1, 1, At, B1); PG8_BAR; PG8_SCHED;
;             PG8_LDB(B0, 1, 0); PG8_LDB(B1, 1, 1); PG8_SCHED; PG8_LDA(At, 1, 0); PG8_STAGE(PG8_SA(0, 1), a2 + hstep, voffA);
;             PG8_WAIT_V(8); PG8_WAIT_L(0); PG8_BAR; PG8_MMA(0, 0, At, B0); PG8_MMA(0, 1, At, B1); PG8_BAR; PG8_SCHED;
	v_mfma_f32_16x16x32_bf16 v[64:67], v[158:161], v[212:215], v[64:67]
	v_mfma_f32_16x16x32_bf16 v[60:63], v[170:173], v[212:215], v[60:63]
	v_mfma_f32_16x16x32_bf16 v[48:51], v[158:161], v[220:223], v[48:51]
	v_mfma_f32_16x16x32_bf16 v[44:47], v[170:173], v[220:223], v[44:47]
	v_mfma_f32_16x16x32_bf16 v[32:35], v[158:161], v[228:231], v[32:35]
	v_mfma_f32_16x16x32_bf16 v[28:31], v[170:173], v[228:231], v[28:31]
	v_mfma_f32_16x16x32_bf16 v[16:19], v[158:161], v[236:239], v[16:19]
	v_mfma_f32_16x16x32_bf16 v[12:15], v[170:173], v[236:239], v[12:15]
	v_mfma_f32_16x16x32_bf16 v[64:67], v[166:169], v[216:219], v[64:67]
	v_mfma_f32_16x16x32_bf16 v[60:63], v[174:177], v[216:219], v[60:63]
	v_mfma_f32_16x16x32_bf16 v[48:51], v[166:169], v[224:227], v[48:51]
	v_mfma_f32_16x16x32_bf16 v[44:47], v[174:177], v[224:227], v[44:47]
	v_mfma_f32_16x16x32_bf16 v[32:35], v[166:169], v[232:235], v[32:35]
	v_mfma_f32_16x16x32_bf16 v[28:31], v[174:177], v[232:235], v[28:31]
	v_mfma_f32_16x16x32_bf16 v[16:19], v[166:169], v[240:243], v[16:19]
	v_mfma_f32_16x16x32_bf16 v[12:15], v[174:177], v[240:243], v[12:15]
	s_setprio 0
	s_setprio 1
	v_mfma_f32_16x16x32_bf16 v[56:59], v[178:181], v[212:215], v[56:59]
	v_mfma_f32_16x16x32_bf16 v[52:55], v[186:189], v[212:215], v[52:55]
	v_mfma_f32_16x16x32_bf16 v[40:43], v[178:181], v[220:223], v[40:43]
	v_mfma_f32_16x16x32_bf16 v[36:39], v[186:189], v[220:223], v[36:39]
	v_mfma_f32_16x16x32_bf16 v[24:27], v[178:181], v[228:231], v[24:27]
	v_mfma_f32_16x16x32_bf16 v[20:23], v[186:189], v[228:231], v[20:23]
	v_mfma_f32_16x16x32_bf16 v[8:11], v[178:181], v[236:239], v[8:11]
	v_mfma_f32_16x16x32_bf16 v[4:7], v[186:189], v[236:239], v[4:7]
	v_mfma_f32_16x16x32_bf16 v[56:59], v[182:185], v[216:219], v[56:59]
	v_mfma_f32_16x16x32_bf16 v[52:55], v[190:193], v[216:219], v[52:55]
	v_mfma_f32_16x16x32_bf16 v[40:43], v[182:185], v[224:227], v[40:43]
	v_mfma_f32_16x16x32_bf16 v[36:39], v[190:193], v[224:227], v[36:39]
	v_mfma_f32_16x16x32_bf16 v[24:27], v[182:185], v[232:235], v[24:27]
	v_mfma_f32_16x16x32_bf16 v[20:23], v[190:193], v[232:235], v[20:23]
	v_mfma_f32_16x16x32_bf16 v[8:11], v[182:185], v[240:243], v[8:11]
	v_mfma_f32_16x16x32_bf16 v[4:7], v[190:193], v[240:243], v[4:7]
	s_barrier
	s_setprio 0
	s_add_i32 s78, 0, 0x18000
	s_add_i32 s79, 0, 0x1c000
	v_add_u32_e32 v174, s78, v147
	v_add_u32_e32 v190, s79, v147
	ds_read_b128 v[158:161], v174
	ds_read_b128 v[166:169], v174 offset:1024
	ds_read_b128 v[170:173], v174 offset:2048
	ds_read_b128 v[174:177], v174 offset:3072
	ds_read_b128 v[178:181], v190
	ds_read_b128 v[182:185], v190 offset:1024
	ds_read_b128 v[186:189], v190 offset:2048
	ds_read_b128 v[190:193], v190 offset:3072
	s_add_u32 s30, s30, 0x80000
	s_addc_u32 s31, s31, 0
	s_mov_b32 m0, s37
	v_lshl_add_u64 v[248:249], s[30:31], 0, v[138:139]
	ds_read_b128 v[212:215], v165 offset:32768
	ds_read_b128 v[216:219], v165 offset:33792
	ds_read_b128 v[220:223], v165 offset:34816
	ds_read_b128 v[224:227], v165 offset:35840
	ds_read_b128 v[228:231], v165 offset:36864
	ds_read_b128 v[232:235], v165 offset:37888
	ds_read_b128 v[236:239], v165 offset:38912
	ds_read_b128 v[240:243], v165 offset:39936
	global_load_lds_dwordx4 v[248:249], off
	v_lshl_add_u64 v[248:249], s[30:31], 0, v[134:135]
	s_mov_b32 m0, s38
	s_nop 0
	global_load_lds_dwordx4 v[248:249], off
	s_waitcnt vmcnt(8)
	s_waitcnt lgkmcnt(0)
	s_setprio 1
	s_barrier
	v_mfma_f32_16x16x32_bf16 v[128:131], v[158:161], v[212:215], v[128:131]
	v_mfma_f32_16x16x32_bf16 v[124:127], v[170:173], v[212:215], v[124:127]
	v_mfma_f32_16x16x32_bf16 v[112:115], v[158:161], v[220:223], v[112:115]
	v_mfma_f32_16x16x32_bf16 v[108:111], v[170:173], v[220:223], v[108:111]
	v_mfma_f32_16x16x32_bf16 v[96:99], v[158:161], v[228:231], v[96:99]
	v_mfma_f32_16x16x32_bf16 v[92:95], v[170:173], v[228:231], v[92:95]
	v_mfma_f32_16x16x32_bf16 v[80:83], v[158:161], v[236:239], v[80:83]
	v_mfma_f32_16x16x32_bf16 v[76:79], v[170:173], v[236:239], v[76:79]
	v_mfma_f32_16x16x32_bf16 v[128:131], v[166:169], v[216:219], v[128:131]
	v_mfma_f32_16x16x32_bf16 v[124:127], v[174:177], v[216:219], v[124:127]
	v_mfma_f32_16x16x32_bf16 v[112:115], v[166:169], v[224:227], v[112:115]
	v_mfma_f32_16x16x32_bf16 v[108:111], v[174:177], v[224:227], v[108:111]
	v_mfma_f32_16x16x32_bf16 v[96:99], v[166:169], v[232:235], v[96:99]
	v_mfma_f32_16x16x32_bf16 v[92:95], v[174:177], v[232:235], v[92:95]
	v_mfma_f32_16x16x32_bf16 v[80:83], v[166:169], v[240:243], v[80:83]
	v_mfma_f32_16x16x32_bf16 v[76:79], v[174:177], v[240:243], v[76:79]
	s_setprio 0
	s_setprio 1
	v_mfma_f32_16x16x32_bf16 v[120:123], v[178:181], v[212:215], v[120:123]
	v_mfma_f32_16x16x32_bf16 v[116:119], v[186:189], v[212:215], v[116:119]
	v_mfma_f32_16x16x32_bf16 v[104:107], v[178:181], v[220:223], v[104:107]
	v_mfma_f32_16x16x32_bf16 v[100:103], v[186:189], v[220:223], v[100:103]
	v_mfma_f32_16x16x32_bf16 v[88:91], v[178:181], v[228:231], v[88:91]
	v_mfma_f32_16x16x32_bf16 v[84:87], v[186:189], v[228:231], v[84:87]
	v_mfma_f32_16x16x32_bf16 v[72:75], v[178:181], v[236:239], v[72:75]
	v_mfma_f32_16x16x32_bf16 v[68:71], v[186:189], v[236:239], v[68:71]
	v_mfma_f32_16x16x32_bf16 v[120:123], v[182:185], v[216:219], v[120:123]
	v_mfma_f32_16x16x32_bf16 v[116:119], v[190:193], v[216:219], v[116:119]
	v_mfma_f32_16x16x32_bf16 v[104:107], v[182:185], v[224:227], v[104:107]
	v_mfma_f32_16x16x32_bf16 v[100:103], v[190:193], v[224:227], v[100:103]
	v_mfma_f32_16x16x32_bf16 v[88:91], v[182:185], v[232:235], v[88:91]
	v_mfma_f32_16x16x32_bf16 v[84:87], v[190:193], v[232:235], v[84:87]
	v_mfma_f32_16x16x32_bf16 v[72:75], v[182:185], v[240:243], v[72:75]
	v_mfma_f32_16x16x32_bf16 v[68:71], v[190:193], v[240:243], v[68:71]
	s_barrier
; #define PG8_STAGE(bufoff, gbase, voff) do { _Pragma("unroll") for (int _i = 0; _i < 2; ++_i) \
;         __builtin_amdgcn_global_load_lds((const unsigned*)((const char*)(gbase) + (voff)[_i]), (LAS unsigned*)(lds + (bufoff) + ldsw + _i * 8192), 16, 0, 0); } while (0)
; #define PG8_LDA(dst, b, h) do { _Pragma("unroll") for (int m = 0; m < 4; ++m) _Pragma("unroll") for (int k = 0; k < 2; ++k) dst[m][k] = *(const LAS bf16x8*)(lds + PG8_SA(b, h) + aoff + m * 2048 + k * 1024); } while (0)
; #define PG8_MMA(ai, bj, At, Bt) do { __builtin_amdgcn_s_setprio(1); _Pragma("unroll") for (int m = 0; m < 4; ++m) _Pragma("unroll") for (int n = 0; n < 2; ++n) _Pragma("unroll") for (int k = 0; k < 2; ++k) \
;         acc[ai][bj][m][n] = __builtin_amdgcn_mfma_f32_16x16x32_bf16(Bt[n][k], At[m][k], acc[ai][bj][m][n], 0, 0, 0); __builtin_amdgcn_s_setprio(0); } while (0)
; #define PG8_WAIT_V(n) asm volatile("s_waitcnt vmcnt(" #n ")" ::: "memory")
; #define PG8_WAIT_L(n) asm volatile("s_waitcnt lgkmcnt(" #n ")" ::: "memory")
; #define PG8_BAR __builtin_amdgcn_s_barrier()
; #define PG8_SCHED __builtin_amdgcn_sched_barrier(0)
; template <class Epi>
; __device__ __forceinline__ void gemm_phase(LAS unsigned char* lds, const Gemm g, const StaticOrder& S, const Epi& E) {
;     ...
;             PG8_LDA(At, 1, 1); PG8_STAGE(PG8_SB(1, 0), b3, voffB); PG8_STAGE(PG8_SB(1, 1), b3 + hstep, voffB); PG8_STAGE(PG8_SA(1, 0), a3, voffA);
;             PG8_WAIT_V(8); PG8_WAIT_L(0); PG8_BAR; PG8_MMA(1, 0, At, B0); PG8_MMA(1, 1, At, B1); PG8_BAR; PG8_SCHED;
;         }
	s_setprio 0
	s_add_i32 s30, s78, s34
	v_lshl_add_u64 v[162:163], v[162:163], 0, s[68:69]
	s_mov_b32 m0, s30
	ds_read_b128 v[212:215], v165 offset:49152
	ds_read_b128 v[216:219], v165 offset:50176
	ds_read_b128 v[220:223], v165 offset:51200
	ds_read_b128 v[224:227], v165 offset:52224
	ds_read_b128 v[228:231], v165 offset:53248
	ds_read_b128 v[232:235], v165 offset:54272
	ds_read_b128 v[236:239], v165 offset:55296
	ds_read_b128 v[240:243], v165 offset:56320
	global_load_lds_dwordx4 v[162:163], off
	s_add_i32 m0, s30, 0x2000
	s_add_u32 s28, s28, 0x80080
	v_lshl_add_u64 v[162:163], v[198:199], 0, s[68:69]
	s_addc_u32 s29, s29, 0
	s_add_i32 s30, s79, s34
	global_load_lds_dwordx4 v[162:163], off
	v_lshl_add_u64 v[162:163], s[28:29], 0, v[136:137]
	s_mov_b32 m0, s30
	s_nop 0
	global_load_lds_dwordx4 v[162:163], off
	v_lshl_add_u64 v[162:163], s[28:29], 0, v[132:133]
	s_add_i32 m0, s30, 0x2000
	s_nop 0
	global_load_lds_dwordx4 v[162:163], off
	v_lshl_add_u64 v[162:163], v[244:245], 0, s[68:69]
	s_mov_b32 m0, s40
	s_nop 0
	global_load_lds_dwordx4 v[162:163], off
	v_lshl_add_u64 v[162:163], v[246:247], 0, s[68:69]
	s_mov_b32 m0, s41
	s_nop 0
	global_load_lds_dwordx4 v[162:163], off
	s_waitcnt vmcnt(8)
	s_waitcnt lgkmcnt(0)
	s_setprio 1
	s_barrier
	v_mfma_f32_16x16x32_bf16 v[64:67], v[158:161], v[212:215], v[64:67]
	v_mfma_f32_16x16x32_bf16 v[60:63], v[170:173], v[212:215], v[60:63]
	v_mfma_f32_16x16x32_bf16 v[48:51], v[158:161], v[220:223], v[48:51]
	v_mfma_f32_16x16x32_bf16 v[44:47], v[170:173], v[220:223], v[44:47]
	v_mfma_f32_16x16x32_bf16 v[32:35], v[158:161], v[228:231], v[32:35]
	v_mfma_f32_16x16x32_bf16 v[28:31], v[170:173], v[228:231], v[28:31]
	v_mfma_f32_16x16x32_bf16 v[16:19], v[158:161], v[236:239], v[16:19]
	v_mfma_f32_16x16x32_bf16 v[12:15], v[170:173], v[236:239], v[12:15]
	v_mfma_f32_16x16x32_bf16 v[64:67], v[166:169], v[216:219], v[64:67]
	v_mfma_f32_16x16x32_bf16 v[60:63], v[174:177], v[216:219], v[60:63]
	v_mfma_f32_16x16x32_bf16 v[48:51], v[166:169], v[224:227], v[48:51]
	v_mfma_f32_16x16x32_bf16 v[44:47], v[174:177], v[224:227], v[44:47]
	v_mfma_f32_16x16x32_bf16 v[32:35], v[166:169], v[232:235], v[32:35]
	v_mfma_f32_16x16x32_bf16 v[28:31], v[174:177], v[232:235], v[28:31]
	v_mfma_f32_16x16x32_bf16 v[16:19], v[166:169], v[240:243], v[16:19]
	v_mfma_f32_16x16x32_bf16 v[12:15], v[174:177], v[240:243], v[12:15]
	s_setprio 0
	s_setprio 1
	v_mfma_f32_16x16x32_bf16 v[56:59], v[178:181], v[212:215], v[56:59]
	v_mfma_f32_16x16x32_bf16 v[52:55], v[186:189], v[212:215], v[52:55]
	v_mfma_f32_16x16x32_bf16 v[40:43], v[178:181], v[220:223], v[40:43]
	v_mfma_f32_16x16x32_bf16 v[36:39], v[186:189], v[220:223], v[36:39]
	v_mfma_f32_16x16x32_bf16 v[24:27], v[178:181], v[228:231], v[24:27]
	v_mfma_f32_16x16x32_bf16 v[20:23], v[186:189], v[228:231], v[20:23]
	v_mfma_f32_16x16x32_bf16 v[8:11], v[178:181], v[236:239], v[8:11]
	v_mfma_f32_16x16x32_bf16 v[4:7], v[186:189], v[236:239], v[4:7]
	v_mfma_f32_16x16x32_bf16 v[56:59], v[182:185], v[216:219], v[56:59]
	v_mfma_f32_16x16x32_bf16 v[52:55], v[190:193], v[216:219], v[52:55]
	v_mfma_f32_16x16x32_bf16 v[40:43], v[182:185], v[224:227], v[40:43]
	v_mfma_f32_16x16x32_bf16 v[36:39], v[190:193], v[224:227], v[36:39]
	v_mfma_f32_16x16x32_bf16 v[24:27], v[182:185], v[232:235], v[24:27]
	v_mfma_f32_16x16x32_bf16 v[20:23], v[190:193], v[232:235], v[20:23]
	v_mfma_f32_16x16x32_bf16 v[8:11], v[182:185], v[240:243], v[8:11]
	v_mfma_f32_16x16x32_bf16 v[4:7], v[190:193], v[240:243], v[4:7]
	s_barrier
	s_setprio 0
	s_add_i32 s80, s80, 2
	s_add_u32 s26, s26, 0x100
	s_addc_u32 s27, s27, 0
	s_add_u32 s76, s76, 0x100
	s_addc_u32 s77, s77, 0
	s_cmp_gt_u32 s80, 29
	s_cbranch_scc0 .LBB0_1741
	s_and_b64 vcc, exec, s[16:17]
	s_cbranch_vccz .LBB0_1744
	s_barrier

; #define PG8_STAGE(bufoff, gbase, voff) do { _Pragma("unroll") for (int _i = 0; _i < 2; ++_i) \
;         __builtin_amdgcn_global_load_lds((const unsigned*)((const char*)(gbase) + (voff)[_i]), (LAS unsigned*)(lds + (bufoff) + ldsw + _i * 8192), 16, 0, 0); } while (0)
; #define PG8_LDA(dst, b, h) do { _Pragma("unroll") for (int m = 0; m < 4; ++m) _Pragma("unroll") for (int k = 0; k < 2; ++k) dst[m][k] = *(const LAS bf16x8*)(lds + PG8_SA(b, h) + aoff + m * 2048 + k * 1024); } while (0)
; #define PG8_LDB(dst, b, h) do { _Pragma("unroll") for (int n = 0; n < 2; ++n) _Pragma("unroll") for (int k = 0; k < 2; ++k) dst[n][k] = *(const LAS bf16x8*)(lds + PG8_SB(b, h) + boff + n * 2048 + k * 1024); } while (0)
; #define PG8_MMA(ai, bj, At, Bt) do { __builtin_amdgcn_s_setprio(1); _Pragma("unroll") for (int m = 0; m < 4; ++m) _Pragma("unroll") for (int n = 0; n < 2; ++n) _Pragma("unroll") for (int k = 0; k < 2; ++k) \
;         acc[ai][bj][m][n] = __builtin_amdgcn_mfma_f32_16x16x32_bf16(Bt[n][k], At[m][k], acc[ai][bj][m][n], 0, 0, 0); __builtin_amdgcn_s_setprio(0); } while (0)
; #define PG8_WAIT_V(n) asm volatile("s_waitcnt vmcnt(" #n ")" ::: "memory")
; #define PG8_WAIT_L(n) asm volatile("s_waitcnt lgkmcnt(" #n ")" ::: "memory")
; #define PG8_BAR __builtin_amdgcn_s_barrier()
; #define PG8_SCHED __builtin_amdgcn_sched_barrier(0)
; template <class Epi>
; __device__ __forceinline__ void gemm_phase(LAS unsigned char* lds, const Gemm g, const StaticOrder& S, const Epi& E) {
;     ...
;             PG8_LDB(B0, 0, 0); PG8_LDB(B1, 0, 1); PG8_SCHED; PG8_LDA(At, 0, 0); PG8_STAGE(PG8_SA(1, 1), a1 + hstep, voffA);
;             PG8_WAIT_V(8); PG8_WAIT_L(0); PG8_BAR; PG8_MMA(0, 0, At, B0); PG8_MMA(0, 1, At, B1); PG8_BAR; PG8_SCHED;
;             PG8_LDA(At, 0, 1); PG8_STAGE(PG8_SB(0, 0), b2, voffB); PG8_STAGE(PG8_SB(0, 1), b2 + hstep, voffB); PG8_STAGE(PG8_SA(0, 0), a2, voffA);
;             PG8_WAIT_V(8); PG8_WAIT_L(0); PG8_BAR; PG8_MMA(1, 0, At, B0); PG8_MMA(1, 1, At, B1); PG8_BAR; PG8_SCHED;
.LBB0_1826:
	s_add_u32 s26, s24, 0xfff80080
	s_addc_u32 s27, s25, -1
	s_add_i32 s77, 0, 0x10000
	s_cmp_eq_u32 s76, 28
	s_cselect_b32 s29, s19, s27
	s_cselect_b32 s28, s45, s26
	s_cselect_b32 s27, s17, s75
	s_cselect_b32 s26, s55, s74
	s_add_i32 s80, 0, 0x14000
	v_add_u32_e32 v174, s77, v147
	v_add_u32_e32 v190, s80, v147
	ds_read_b128 v[158:161], v174
	ds_read_b128 v[166:169], v174 offset:1024
	ds_read_b128 v[170:173], v174 offset:2048
	ds_read_b128 v[174:177], v174 offset:3072
	ds_read_b128 v[178:181], v190
	ds_read_b128 v[182:185], v190 offset:1024
	ds_read_b128 v[186:189], v190 offset:2048
	ds_read_b128 v[190:193], v190 offset:3072
	v_lshl_add_u64 v[198:199], s[24:25], 0, v[140:141]
	s_add_i32 m0, s31, 0xc000
	ds_read_b128 v[212:215], v165
	ds_read_b128 v[216:219], v165 offset:1024
	ds_read_b128 v[220:223], v165 offset:2048
	ds_read_b128 v[224:227], v165 offset:3072
	ds_read_b128 v[228:231], v165 offset:4096
	ds_read_b128 v[232:235], v165 offset:5120
	ds_read_b128 v[236:239], v165 offset:6144
	ds_read_b128 v[240:243], v165 offset:7168
	global_load_lds_dwordx4 v[198:199], off
	v_lshl_add_u64 v[198:199], s[24:25], 0, v[156:157]
	s_add_i32 m0, s31, 0xe000
	s_nop 0
	global_load_lds_dwordx4 v[198:199], off
	s_waitcnt vmcnt(8)
	s_waitcnt lgkmcnt(0)
	s_setprio 1
	s_barrier
	v_mfma_f32_16x16x32_bf16 v[128:131], v[158:161], v[212:215], v[128:131]
	v_mfma_f32_16x16x32_bf16 v[124:127], v[170:173], v[212:215], v[124:127]
	v_mfma_f32_16x16x32_bf16 v[112:115], v[158:161], v[220:223], v[112:115]
	v_mfma_f32_16x16x32_bf16 v[108:111], v[170:173], v[220:223], v[108:111]
	v_mfma_f32_16x16x32_bf16 v[96:99], v[158:161], v[228:231], v[96:99]
	v_mfma_f32_16x16x32_bf16 v[92:95], v[170:173], v[228:231], v[92:95]
	v_mfma_f32_16x16x32_bf16 v[80:83], v[158:161], v[236:239], v[80:83]
	v_mfma_f32_16x16x32_bf16 v[76:79], v[170:173], v[236:239], v[76:79]
	v_mfma_f32_16x16x32_bf16 v[128:131], v[166:169], v[216:219], v[128:131]
	v_mfma_f32_16x16x32_bf16 v[124:127], v[174:177], v[216:219], v[124:127]
	v_mfma_f32_16x16x32_bf16 v[112:115], v[166:169], v[224:227], v[112:115]
	v_mfma_f32_16x16x32_bf16 v[108:111], v[174:177], v[224:227], v[108:111]
	v_mfma_f32_16x16x32_bf16 v[96:99], v[166:169], v[232:235], v[96:99]
	v_mfma_f32_16x16x32_bf16 v[92:95], v[174:177], v[232:235], v[92:95]
	v_mfma_f32_16x16x32_bf16 v[80:83], v[166:169], v[240:243], v[80:83]
	v_mfma_f32_16x16x32_bf16 v[76:79], v[174:177], v[240:243], v[76:79]
	s_setprio 0
	s_setprio 1
	v_mfma_f32_16x16x32_bf16 v[120:123], v[178:181], v[212:215], v[120:123]
	v_mfma_f32_16x16x32_bf16 v[116:119], v[186:189], v[212:215], v[116:119]
	v_mfma_f32_16x16x32_bf16 v[104:107], v[178:181], v[220:223], v[104:107]
	v_mfma_f32_16x16x32_bf16 v[100:103], v[186:189], v[220:223], v[100:103]
	v_mfma_f32_16x16x32_bf16 v[88:91], v[178:181], v[228:231], v[88:91]
	v_mfma_f32_16x16x32_bf16 v[84:87], v[186:189], v[228:231], v[84:87]
	v_mfma_f32_16x16x32_bf16 v[72:75], v[178:181], v[236:239], v[72:75]
	v_mfma_f32_16x16x32_bf16 v[68:71], v[186:189], v[236:239], v[68:71]
	v_mfma_f32_16x16x32_bf16 v[120:123], v[182:185], v[216:219], v[120:123]
	v_mfma_f32_16x16x32_bf16 v[116:119], v[190:193], v[216:219], v[116:119]
	v_mfma_f32_16x16x32_bf16 v[104:107], v[182:185], v[224:227], v[104:107]
	v_mfma_f32_16x16x32_bf16 v[100:103], v[190:193], v[224:227], v[100:103]
	v_mfma_f32_16x16x32_bf16 v[88:91], v[182:185], v[232:235], v[88:91]
	v_mfma_f32_16x16x32_bf16 v[84:87], v[190:193], v[232:235], v[84:87]
	v_mfma_f32_16x16x32_bf16 v[72:75], v[182:185], v[240:243], v[72:75]
	v_mfma_f32_16x16x32_bf16 v[68:71], v[190:193], v[240:243], v[68:71]
	s_barrier
	s_setprio 0
	s_add_i32 s77, s77, s30
	v_lshl_add_u64 v[198:199], s[26:27], 0, v[136:137]
	s_mov_b32 m0, s77
	ds_read_b128 v[212:215], v165 offset:16384
	ds_read_b128 v[216:219], v165 offset:17408
	ds_read_b128 v[220:223], v165 offset:18432
	ds_read_b128 v[224:227], v165 offset:19456
	ds_read_b128 v[228:231], v165 offset:20480
	ds_read_b128 v[232:235], v165 offset:21504
	ds_read_b128 v[236:239], v165 offset:22528
	ds_read_b128 v[240:243], v165 offset:23552
	global_load_lds_dwordx4 v[198:199], off
	s_add_i32 m0, s77, 0x2000
	s_add_u32 s78, s26, 0x80000
	v_lshl_add_u64 v[244:245], s[26:27], 0, v[132:133]
	s_addc_u32 s79, s27, 0
	s_add_i32 s77, s80, s30
	global_load_lds_dwordx4 v[244:245], off
	v_lshl_add_u64 v[246:247], s[78:79], 0, v[136:137]
	s_mov_b32 m0, s77
	v_lshl_add_u64 v[248:249], s[28:29], 0, v[134:135]
	global_load_lds_dwordx4 v[246:247], off
	v_lshl_add_u64 v[246:247], s[78:79], 0, v[132:133]
	s_add_i32 m0, s77, 0x2000
	s_nop 0
	global_load_lds_dwordx4 v[246:247], off
	v_lshl_add_u64 v[246:247], s[28:29], 0, v[138:139]
	s_mov_b32 m0, s31
	s_nop 0
	global_load_lds_dwordx4 v[246:247], off
	s_mov_b32 m0, s34
	s_nop 0
	global_load_lds_dwordx4 v[248:249], off
	s_waitcnt vmcnt(8)
	s_waitcnt lgkmcnt(0)
	s_setprio 1
	s_barrier
; #define PG8_STAGE(bufoff, gbase, voff) do { _Pragma("unroll") for (int _i = 0; _i < 2; ++_i) \
;         __builtin_amdgcn_global_load_lds((const unsigned*)((const char*)(gbase) + (voff)[_i]), (LAS unsigned*)(lds + (bufoff) + ldsw + _i * 8192), 16, 0, 0); } while (0)
; #define PG8_LDA(dst, b, h) do { _Pragma("unroll") for (int m = 0; m < 4; ++m) _Pragma("unroll") for (int k = 0; k < 2; ++k) dst[m][k] = *(const LAS bf16x8*)(lds + PG8_SA(b, h) + aoff + m * 2048 + k * 1024); } while (0)
; #define PG8_LDB(dst, b, h) do { _Pragma("unroll") for (int n = 0; n < 2; ++n) _Pragma("unroll") for (int k = 0; k < 2; ++k) dst[n][k] = *(const LAS bf16x8*)(lds + PG8_SB(b, h) + boff + n * 2048 + k * 1024); } while (0)
; #define PG8_MMA(ai, bj, At, Bt) do { __builtin_amdgcn_s_setprio(1); _Pragma("unroll") for (int m = 0; m < 4; ++m) _Pragma("unroll") for (int n = 0; n < 2; ++n) _Pragma("unroll") for (int k = 0; k < 2; ++k) \
;         acc[ai][bj][m][n] = __builtin_amdgcn_mfma_f32_16x16x32_bf16(Bt[n][k], At[m][k], acc[ai][bj][m][n], 0, 0, 0); __builtin_amdgcn_s_setprio(0); } while (0)
; #define PG8_WAIT_V(n) asm volatile("s_waitcnt vmcnt(" #n ")" ::: "memory")
; #define PG8_WAIT_L(n) asm volatile("s_waitcnt lgkmcnt(" #n ")" ::: "memory")
; #define PG8_BAR __builtin_amdgcn_s_barrier()
; #define PG8_SCHED __builtin_amdgcn_sched_barrier(0)
; template <class Epi>
; __device__ __forceinline__ void gemm_phase(LAS unsigned char* lds, const Gemm g, const StaticOrder& S, const Epi& E) {
;     ...
;             PG8_WAIT_V(8); PG8_WAIT_L(0); PG8_BAR; PG8_MMA(1, 0, At, B0); PG8_MMA(1, 1, At, B1); PG8_BAR; PG8_SCHED;
;             PG8_LDB(B0, 1, 0); PG8_LDB(B1, 1, 1); PG8_SCHED; PG8_LDA(At, 1, 0); PG8_STAGE(PG8_SA(0, 1), a2 + hstep, voffA);
;             PG8_WAIT_V(8); PG8_WAIT_L(0); PG8_BAR; PG8_MMA(0, 0, At, B0); PG8_MMA(0, 1, At, B1); PG8_BAR; PG8_SCHED;
	v_mfma_f32_16x16x32_bf16 v[64:67], v[158:161], v[212:215], v[64:67]
	v_mfma_f32_16x16x32_bf16 v[60:63], v[170:173], v[212:215], v[60:63]
	v_mfma_f32_16x16x32_bf16 v[56:59], v[158:161], v[220:223], v[56:59]
	v_mfma_f32_16x16x32_bf16 v[48:51], v[170:173], v[220:223], v[48:51]
	v_mfma_f32_16x16x32_bf16 v[40:43], v[158:161], v[228:231], v[40:43]
	v_mfma_f32_16x16x32_bf16 v[32:35], v[170:173], v[228:231], v[32:35]
	v_mfma_f32_16x16x32_bf16 v[20:23], v[158:161], v[236:239], v[20:23]
	v_mfma_f32_16x16x32_bf16 v[12:15], v[170:173], v[236:239], v[12:15]
	v_mfma_f32_16x16x32_bf16 v[64:67], v[166:169], v[216:219], v[64:67]
	v_mfma_f32_16x16x32_bf16 v[60:63], v[174:177], v[216:219], v[60:63]
	v_mfma_f32_16x16x32_bf16 v[56:59], v[166:169], v[224:227], v[56:59]
	v_mfma_f32_16x16x32_bf16 v[48:51], v[174:177], v[224:227], v[48:51]
	v_mfma_f32_16x16x32_bf16 v[40:43], v[166:169], v[232:235], v[40:43]
	v_mfma_f32_16x16x32_bf16 v[32:35], v[174:177], v[232:235], v[32:35]
	v_mfma_f32_16x16x32_bf16 v[20:23], v[166:169], v[240:243], v[20:23]
	v_mfma_f32_16x16x32_bf16 v[12:15], v[174:177], v[240:243], v[12:15]
	s_setprio 0
	s_setprio 1
	v_mfma_f32_16x16x32_bf16 v[52:55], v[178:181], v[212:215], v[52:55]
	v_mfma_f32_16x16x32_bf16 v[44:47], v[186:189], v[212:215], v[44:47]
	v_mfma_f32_16x16x32_bf16 v[36:39], v[178:181], v[220:223], v[36:39]
	v_mfma_f32_16x16x32_bf16 v[28:31], v[186:189], v[220:223], v[28:31]
	v_mfma_f32_16x16x32_bf16 v[24:27], v[178:181], v[228:231], v[24:27]
	v_mfma_f32_16x16x32_bf16 v[16:19], v[186:189], v[228:231], v[16:19]
	v_mfma_f32_16x16x32_bf16 v[8:11], v[178:181], v[236:239], v[8:11]
	v_mfma_f32_16x16x32_bf16 v[4:7], v[186:189], v[236:239], v[4:7]
	v_mfma_f32_16x16x32_bf16 v[52:55], v[182:185], v[216:219], v[52:55]
	v_mfma_f32_16x16x32_bf16 v[44:47], v[190:193], v[216:219], v[44:47]
	v_mfma_f32_16x16x32_bf16 v[36:39], v[182:185], v[224:227], v[36:39]
	v_mfma_f32_16x16x32_bf16 v[28:31], v[190:193], v[224:227], v[28:31]
	v_mfma_f32_16x16x32_bf16 v[24:27], v[182:185], v[232:235], v[24:27]
	v_mfma_f32_16x16x32_bf16 v[16:19], v[190:193], v[232:235], v[16:19]
	v_mfma_f32_16x16x32_bf16 v[8:11], v[182:185], v[240:243], v[8:11]
	v_mfma_f32_16x16x32_bf16 v[4:7], v[190:193], v[240:243], v[4:7]
	s_barrier
	s_setprio 0
	s_add_i32 s77, 0, 0x18000
	s_add_i32 s78, 0, 0x1c000
	v_add_u32_e32 v174, s77, v147
	v_add_u32_e32 v190, s78, v147
	ds_read_b128 v[158:161], v174
	ds_read_b128 v[166:169], v174 offset:1024
	ds_read_b128 v[170:173], v174 offset:2048
	ds_read_b128 v[174:177], v174 offset:3072
	ds_read_b128 v[178:181], v190
	ds_read_b128 v[182:185], v190 offset:1024
	ds_read_b128 v[186:189], v190 offset:2048
	ds_read_b128 v[190:193], v190 offset:3072
	s_add_u32 s28, s28, 0x80000
	s_addc_u32 s29, s29, 0
	s_mov_b32 m0, s35
	v_lshl_add_u64 v[250:251], s[28:29], 0, v[138:139]
	ds_read_b128 v[212:215], v165 offset:32768
	ds_read_b128 v[216:219], v165 offset:33792
	ds_read_b128 v[220:223], v165 offset:34816
	ds_read_b128 v[224:227], v165 offset:35840
	ds_read_b128 v[228:231], v165 offset:36864
	ds_read_b128 v[232:235], v165 offset:37888
	ds_read_b128 v[236:239], v165 offset:38912
	ds_read_b128 v[240:243], v165 offset:39936
	global_load_lds_dwordx4 v[250:251], off
	v_lshl_add_u64 v[250:251], s[28:29], 0, v[134:135]
	s_mov_b32 m0, s36
	s_nop 0
	global_load_lds_dwordx4 v[250:251], off
	s_waitcnt vmcnt(8)
	s_waitcnt lgkmcnt(0)
	s_setprio 1
	s_barrier
	v_mfma_f32_16x16x32_bf16 v[128:131], v[158:161], v[212:215], v[128:131]
	v_mfma_f32_16x16x32_bf16 v[124:127], v[170:173], v[212:215], v[124:127]
	v_mfma_f32_16x16x32_bf16 v[112:115], v[158:161], v[220:223], v[112:115]
	v_mfma_f32_16x16x32_bf16 v[108:111], v[170:173], v[220:223], v[108:111]
	v_mfma_f32_16x16x32_bf16 v[96:99], v[158:161], v[228:231], v[96:99]
	v_mfma_f32_16x16x32_bf16 v[92:95], v[170:173], v[228:231], v[92:95]
	v_mfma_f32_16x16x32_bf16 v[80:83], v[158:161], v[236:239], v[80:83]
	v_mfma_f32_16x16x32_bf16 v[76:79], v[170:173], v[236:239], v[76:79]
	v_mfma_f32_16x16x32_bf16 v[128:131], v[166:169], v[216:219], v[128:131]
	v_mfma_f32_16x16x32_bf16 v[124:127], v[174:177], v[216:219], v[124:127]
	v_mfma_f32_16x16x32_bf16 v[112:115], v[166:169], v[224:227], v[112:115]
	v_mfma_f32_16x16x32_bf16 v[108:111], v[174:177], v[224:227], v[108:111]
	v_mfma_f32_16x16x32_bf16 v[96:99], v[166:169], v[232:235], v[96:99]
	v_mfma_f32_16x16x32_bf16 v[92:95], v[174:177], v[232:235], v[92:95]
	v_mfma_f32_16x16x32_bf16 v[80:83], v[166:169], v[240:243], v[80:83]
	v_mfma_f32_16x16x32_bf16 v[76:79], v[174:177], v[240:243], v[76:79]
	s_setprio 0
	s_setprio 1
	v_mfma_f32_16x16x32_bf16 v[120:123], v[178:181], v[212:215], v[120:123]
	v_mfma_f32_16x16x32_bf16 v[116:119], v[186:189], v[212:215], v[116:119]
	v_mfma_f32_16x16x32_bf16 v[104:107], v[178:181], v[220:223], v[104:107]
	v_mfma_f32_16x16x32_bf16 v[100:103], v[186:189], v[220:223], v[100:103]
	v_mfma_f32_16x16x32_bf16 v[88:91], v[178:181], v[228:231], v[88:91]
	v_mfma_f32_16x16x32_bf16 v[84:87], v[186:189], v[228:231], v[84:87]
	v_mfma_f32_16x16x32_bf16 v[72:75], v[178:181], v[236:239], v[72:75]
	v_mfma_f32_16x16x32_bf16 v[68:71], v[186:189], v[236:239], v[68:71]
	v_mfma_f32_16x16x32_bf16 v[120:123], v[182:185], v[216:219], v[120:123]
	v_mfma_f32_16x16x32_bf16 v[116:119], v[190:193], v[216:219], v[116:119]
	v_mfma_f32_16x16x32_bf16 v[104:107], v[182:185], v[224:227], v[104:107]
	v_mfma_f32_16x16x32_bf16 v[100:103], v[190:193], v[224:227], v[100:103]
	v_mfma_f32_16x16x32_bf16 v[88:91], v[182:185], v[232:235], v[88:91]
	v_mfma_f32_16x16x32_bf16 v[84:87], v[190:193], v[232:235], v[84:87]
	v_mfma_f32_16x16x32_bf16 v[72:75], v[182:185], v[240:243], v[72:75]
	v_mfma_f32_16x16x32_bf16 v[68:71], v[190:193], v[240:243], v[68:71]
	s_barrier
; #define PG8_STAGE(bufoff, gbase, voff) do { _Pragma("unroll") for (int _i = 0; _i < 2; ++_i) \
;         __builtin_amdgcn_global_load_lds((const unsigned*)((const char*)(gbase) + (voff)[_i]), (LAS unsigned*)(lds + (bufoff) + ldsw + _i * 8192), 16, 0, 0); } while (0)
; #define PG8_LDA(dst, b, h) do { _Pragma("unroll") for (int m = 0; m < 4; ++m) _Pragma("unroll") for (int k = 0; k < 2; ++k) dst[m][k] = *(const LAS bf16x8*)(lds + PG8_SA(b, h) + aoff + m * 2048 + k * 1024); } while (0)
; #define PG8_MMA(ai, bj, At, Bt) do { __builtin_amdgcn_s_setprio(1); _Pragma("unroll") for (int m = 0; m < 4; ++m) _Pragma("unroll") for (int n = 0; n < 2; ++n) _Pragma("unroll") for (int k = 0; k < 2; ++k) \
;         acc[ai][bj][m][n] = __builtin_amdgcn_mfma_f32_16x16x32_bf16(Bt[n][k], At[m][k], acc[ai][bj][m][n], 0, 0, 0); __builtin_amdgcn_s_setprio(0); } while (0)
; #define PG8_WAIT_V(n) asm volatile("s_waitcnt vmcnt(" #n ")" ::: "memory")
; #define PG8_WAIT_L(n) asm volatile("s_waitcnt lgkmcnt(" #n ")" ::: "memory")
; #define PG8_BAR __builtin_amdgcn_s_barrier()
; #define PG8_SCHED __builtin_amdgcn_sched_barrier(0)
; template <class Epi>
; __device__ __forceinline__ void gemm_phase(LAS unsigned char* lds, const Gemm g, const StaticOrder& S, const Epi& E) {
;     ...
;             PG8_LDA(At, 1, 1); PG8_STAGE(PG8_SB(1, 0), b3, voffB); PG8_STAGE(PG8_SB(1, 1), b3 + hstep, voffB); PG8_STAGE(PG8_SA(1, 0), a3, voffA);
;             PG8_WAIT_V(8); PG8_WAIT_L(0); PG8_BAR; PG8_MMA(1, 0, At, B0); PG8_MMA(1, 1, At, B1); PG8_BAR; PG8_SCHED;
;         }
	s_setprio 0
	s_add_i32 s28, s77, s30
	v_lshl_add_u64 v[198:199], v[198:199], 0, s[68:69]
	s_mov_b32 m0, s28
	ds_read_b128 v[212:215], v165 offset:49152
	ds_read_b128 v[216:219], v165 offset:50176
	ds_read_b128 v[220:223], v165 offset:51200
	ds_read_b128 v[224:227], v165 offset:52224
	ds_read_b128 v[228:231], v165 offset:53248
	ds_read_b128 v[232:235], v165 offset:54272
	ds_read_b128 v[236:239], v165 offset:55296
	ds_read_b128 v[240:243], v165 offset:56320
	global_load_lds_dwordx4 v[198:199], off
	s_add_i32 m0, s28, 0x2000
	s_add_u32 s26, s26, 0x80080
	v_lshl_add_u64 v[198:199], v[244:245], 0, s[68:69]
	s_addc_u32 s27, s27, 0
	s_add_i32 s28, s78, s30
	global_load_lds_dwordx4 v[198:199], off
	v_lshl_add_u64 v[198:199], s[26:27], 0, v[136:137]
	s_mov_b32 m0, s28
	s_nop 0
	global_load_lds_dwordx4 v[198:199], off
	v_lshl_add_u64 v[198:199], s[26:27], 0, v[132:133]
	s_add_i32 m0, s28, 0x2000
	s_nop 0
	global_load_lds_dwordx4 v[198:199], off
	v_lshl_add_u64 v[198:199], v[246:247], 0, s[68:69]
	s_mov_b32 m0, s37
	s_nop 0
	global_load_lds_dwordx4 v[198:199], off
	v_lshl_add_u64 v[198:199], v[248:249], 0, s[68:69]
	s_mov_b32 m0, s38
	s_nop 0
	global_load_lds_dwordx4 v[198:199], off
	s_waitcnt vmcnt(8)
	s_waitcnt lgkmcnt(0)
	s_setprio 1
	s_barrier
	v_mfma_f32_16x16x32_bf16 v[64:67], v[158:161], v[212:215], v[64:67]
	v_mfma_f32_16x16x32_bf16 v[60:63], v[170:173], v[212:215], v[60:63]
	v_mfma_f32_16x16x32_bf16 v[56:59], v[158:161], v[220:223], v[56:59]
	v_mfma_f32_16x16x32_bf16 v[48:51], v[170:173], v[220:223], v[48:51]
	v_mfma_f32_16x16x32_bf16 v[40:43], v[158:161], v[228:231], v[40:43]
	v_mfma_f32_16x16x32_bf16 v[32:35], v[170:173], v[228:231], v[32:35]
	v_mfma_f32_16x16x32_bf16 v[20:23], v[158:161], v[236:239], v[20:23]
	v_mfma_f32_16x16x32_bf16 v[12:15], v[170:173], v[236:239], v[12:15]
	v_mfma_f32_16x16x32_bf16 v[64:67], v[166:169], v[216:219], v[64:67]
	v_mfma_f32_16x16x32_bf16 v[60:63], v[174:177], v[216:219], v[60:63]
	v_mfma_f32_16x16x32_bf16 v[56:59], v[166:169], v[224:227], v[56:59]
	v_mfma_f32_16x16x32_bf16 v[48:51], v[174:177], v[224:227], v[48:51]
	v_mfma_f32_16x16x32_bf16 v[40:43], v[166:169], v[232:235], v[40:43]
	v_mfma_f32_16x16x32_bf16 v[32:35], v[174:177], v[232:235], v[32:35]
	v_mfma_f32_16x16x32_bf16 v[20:23], v[166:169], v[240:243], v[20:23]
	v_mfma_f32_16x16x32_bf16 v[12:15], v[174:177], v[240:243], v[12:15]
	s_setprio 0
	s_setprio 1
	v_mfma_f32_16x16x32_bf16 v[52:55], v[178:181], v[212:215], v[52:55]
	v_mfma_f32_16x16x32_bf16 v[44:47], v[186:189], v[212:215], v[44:47]
	v_mfma_f32_16x16x32_bf16 v[36:39], v[178:181], v[220:223], v[36:39]
	v_mfma_f32_16x16x32_bf16 v[28:31], v[186:189], v[220:223], v[28:31]
	v_mfma_f32_16x16x32_bf16 v[24:27], v[178:181], v[228:231], v[24:27]
	v_mfma_f32_16x16x32_bf16 v[16:19], v[186:189], v[228:231], v[16:19]
	v_mfma_f32_16x16x32_bf16 v[8:11], v[178:181], v[236:239], v[8:11]
	v_mfma_f32_16x16x32_bf16 v[4:7], v[186:189], v[236:239], v[4:7]
	v_mfma_f32_16x16x32_bf16 v[52:55], v[182:185], v[216:219], v[52:55]
	v_mfma_f32_16x16x32_bf16 v[44:47], v[190:193], v[216:219], v[44:47]
	v_mfma_f32_16x16x32_bf16 v[36:39], v[182:185], v[224:227], v[36:39]
	v_mfma_f32_16x16x32_bf16 v[28:31], v[190:193], v[224:227], v[28:31]
	v_mfma_f32_16x16x32_bf16 v[24:27], v[182:185], v[232:235], v[24:27]
	v_mfma_f32_16x16x32_bf16 v[16:19], v[190:193], v[232:235], v[16:19]
	v_mfma_f32_16x16x32_bf16 v[8:11], v[182:185], v[240:243], v[8:11]
	v_mfma_f32_16x16x32_bf16 v[4:7], v[190:193], v[240:243], v[4:7]
	s_barrier
	s_setprio 0
	s_add_i32 s76, s76, 2
	s_add_u32 s24, s24, 0x100
	s_addc_u32 s25, s25, 0
	s_add_u32 s74, s74, 0x100
	s_addc_u32 s75, s75, 0
	s_cmp_gt_u32 s76, 29
	s_cbranch_scc0 .LBB0_1826
	s_and_b64 vcc, exec, s[14:15]
	s_cbranch_vccz .LBB0_1829
	s_barrier

; #define PG8_STAGE(bufoff, gbase, voff) do { _Pragma("unroll") for (int _i = 0; _i < 2; ++_i) \
;         __builtin_amdgcn_global_load_lds((const unsigned*)((const char*)(gbase) + (voff)[_i]), (LAS unsigned*)(lds + (bufoff) + ldsw + _i * 8192), 16, 0, 0); } while (0)
; #define PG8_LDA(dst, b, h) do { _Pragma("unroll") for (int m = 0; m < 4; ++m) _Pragma("unroll") for (int k = 0; k < 2; ++k) dst[m][k] = *(const LAS bf16x8*)(lds + PG8_SA(b, h) + aoff + m * 2048 + k * 1024); } while (0)
; #define PG8_LDB(dst, b, h) do { _Pragma("unroll") for (int n = 0; n < 2; ++n) _Pragma("unroll") for (int k = 0; k < 2; ++k) dst[n][k] = *(const LAS bf16x8*)(lds + PG8_SB(b, h) + boff + n * 2048 + k * 1024); } while (0)
; #define PG8_MMA(ai, bj, At, Bt) do { __builtin_amdgcn_s_setprio(1); _Pragma("unroll") for (int m = 0; m < 4; ++m) _Pragma("unroll") for (int n = 0; n < 2; ++n) _Pragma("unroll") for (int k = 0; k < 2; ++k) \
;         acc[ai][bj][m][n] = __builtin_amdgcn_mfma_f32_16x16x32_bf16(Bt[n][k], At[m][k], acc[ai][bj][m][n], 0, 0, 0); __builtin_amdgcn_s_setprio(0); } while (0)
; #define PG8_WAIT_V(n) asm volatile("s_waitcnt vmcnt(" #n ")" ::: "memory")
; #define PG8_WAIT_L(n) asm volatile("s_waitcnt lgkmcnt(" #n ")" ::: "memory")
; #define PG8_BAR __builtin_amdgcn_s_barrier()
; #define PG8_SCHED __builtin_amdgcn_sched_barrier(0)
; template <class Epi>
; __device__ __forceinline__ void gemm_phase(LAS unsigned char* lds, const Gemm g, const StaticOrder& S, const Epi& E) {
;     ...
;             PG8_LDB(B0, 0, 0); PG8_LDB(B1, 0, 1); PG8_SCHED; PG8_LDA(At, 0, 0); PG8_STAGE(PG8_SA(1, 1), a1 + hstep, voffA);
;             PG8_WAIT_V(8); PG8_WAIT_L(0); PG8_BAR; PG8_MMA(0, 0, At, B0); PG8_MMA(0, 1, At, B1); PG8_BAR; PG8_SCHED;
;             PG8_LDA(At, 0, 1); PG8_STAGE(PG8_SB(0, 0), b2, voffB); PG8_STAGE(PG8_SB(0, 1), b2 + hstep, voffB); PG8_STAGE(PG8_SA(0, 0), a2, voffA);
;             PG8_WAIT_V(8); PG8_WAIT_L(0); PG8_BAR; PG8_MMA(1, 0, At, B0); PG8_MMA(1, 1, At, B1); PG8_BAR; PG8_SCHED;
.LBB0_1972:
	s_add_u32 s24, s22, 0xffe00080
	s_addc_u32 s25, s23, -1
	s_add_i32 s75, 0, 0x10000
	s_cmpk_eq_i32 s74, 0x7c
	s_cselect_b32 s27, s17, s25
	s_cselect_b32 s26, s45, s24
	v_add_u32_e32 v162, s75, v147
	s_cselect_b32 s25, s15, s61
	s_cselect_b32 s24, s55, s60
	s_add_i32 s78, 0, 0x14000
	ds_read_b128 v[158:161], v162
	ds_read_b128 v[166:169], v162 offset:1024
	ds_read_b128 v[170:173], v162 offset:2048
	ds_read_b128 v[174:177], v162 offset:3072
	v_add_u32_e32 v162, s78, v147
	ds_read_b128 v[178:181], v162
	ds_read_b128 v[182:185], v162 offset:1024
	ds_read_b128 v[186:189], v162 offset:2048
	ds_read_b128 v[190:193], v162 offset:3072
	v_lshl_add_u64 v[162:163], s[22:23], 0, v[140:141]
	s_add_i32 m0, s31, 0xc000
	ds_read_b128 v[212:215], v165
	ds_read_b128 v[216:219], v165 offset:1024
	ds_read_b128 v[220:223], v165 offset:2048
	ds_read_b128 v[224:227], v165 offset:3072
	ds_read_b128 v[228:231], v165 offset:4096
	ds_read_b128 v[232:235], v165 offset:5120
	ds_read_b128 v[236:239], v165 offset:6144
	ds_read_b128 v[240:243], v165 offset:7168
	global_load_lds_dwordx4 v[162:163], off
	v_lshl_add_u64 v[162:163], s[22:23], 0, v[156:157]
	s_add_i32 m0, s31, 0xe000
	s_nop 0
	global_load_lds_dwordx4 v[162:163], off
	s_waitcnt vmcnt(8)
	s_waitcnt lgkmcnt(0)
	s_setprio 1
	s_barrier
	v_mfma_f32_16x16x32_bf16 v[128:131], v[158:161], v[212:215], v[128:131]
	v_mfma_f32_16x16x32_bf16 v[124:127], v[170:173], v[212:215], v[124:127]
	v_mfma_f32_16x16x32_bf16 v[112:115], v[158:161], v[220:223], v[112:115]
	v_mfma_f32_16x16x32_bf16 v[108:111], v[170:173], v[220:223], v[108:111]
	v_mfma_f32_16x16x32_bf16 v[96:99], v[158:161], v[228:231], v[96:99]
	v_mfma_f32_16x16x32_bf16 v[92:95], v[170:173], v[228:231], v[92:95]
	v_mfma_f32_16x16x32_bf16 v[80:83], v[158:161], v[236:239], v[80:83]
	v_mfma_f32_16x16x32_bf16 v[76:79], v[170:173], v[236:239], v[76:79]
	v_mfma_f32_16x16x32_bf16 v[128:131], v[166:169], v[216:219], v[128:131]
	v_mfma_f32_16x16x32_bf16 v[124:127], v[174:177], v[216:219], v[124:127]
	v_mfma_f32_16x16x32_bf16 v[112:115], v[166:169], v[224:227], v[112:115]
	v_mfma_f32_16x16x32_bf16 v[108:111], v[174:177], v[224:227], v[108:111]
	v_mfma_f32_16x16x32_bf16 v[96:99], v[166:169], v[232:235], v[96:99]
	v_mfma_f32_16x16x32_bf16 v[92:95], v[174:177], v[232:235], v[92:95]
	v_mfma_f32_16x16x32_bf16 v[80:83], v[166:169], v[240:243], v[80:83]
	v_mfma_f32_16x16x32_bf16 v[76:79], v[174:177], v[240:243], v[76:79]
	s_setprio 0
	s_setprio 1
	v_mfma_f32_16x16x32_bf16 v[120:123], v[178:181], v[212:215], v[120:123]
	v_mfma_f32_16x16x32_bf16 v[116:119], v[186:189], v[212:215], v[116:119]
	v_mfma_f32_16x16x32_bf16 v[104:107], v[178:181], v[220:223], v[104:107]
	v_mfma_f32_16x16x32_bf16 v[100:103], v[186:189], v[220:223], v[100:103]
	v_mfma_f32_16x16x32_bf16 v[88:91], v[178:181], v[228:231], v[88:91]
	v_mfma_f32_16x16x32_bf16 v[84:87], v[186:189], v[228:231], v[84:87]
	v_mfma_f32_16x16x32_bf16 v[72:75], v[178:181], v[236:239], v[72:75]
	v_mfma_f32_16x16x32_bf16 v[68:71], v[186:189], v[236:239], v[68:71]
	v_mfma_f32_16x16x32_bf16 v[120:123], v[182:185], v[216:219], v[120:123]
	v_mfma_f32_16x16x32_bf16 v[116:119], v[190:193], v[216:219], v[116:119]
	v_mfma_f32_16x16x32_bf16 v[104:107], v[182:185], v[224:227], v[104:107]
	v_mfma_f32_16x16x32_bf16 v[100:103], v[190:193], v[224:227], v[100:103]
	v_mfma_f32_16x16x32_bf16 v[88:91], v[182:185], v[232:235], v[88:91]
	v_mfma_f32_16x16x32_bf16 v[84:87], v[190:193], v[232:235], v[84:87]
	v_mfma_f32_16x16x32_bf16 v[72:75], v[182:185], v[240:243], v[72:75]
	v_mfma_f32_16x16x32_bf16 v[68:71], v[190:193], v[240:243], v[68:71]
	s_barrier
	s_setprio 0
	s_add_i32 s75, s75, s30
	v_lshl_add_u64 v[162:163], s[24:25], 0, v[136:137]
	s_mov_b32 m0, s75
	ds_read_b128 v[212:215], v165 offset:16384
	ds_read_b128 v[216:219], v165 offset:17408
	ds_read_b128 v[220:223], v165 offset:18432
	ds_read_b128 v[224:227], v165 offset:19456
	ds_read_b128 v[228:231], v165 offset:20480
	ds_read_b128 v[232:235], v165 offset:21504
	ds_read_b128 v[236:239], v165 offset:22528
	ds_read_b128 v[240:243], v165 offset:23552
	global_load_lds_dwordx4 v[162:163], off
	s_add_i32 m0, s75, 0x2000
	s_add_u32 s76, s24, 0x200000
	v_lshl_add_u64 v[198:199], s[24:25], 0, v[132:133]
	s_addc_u32 s77, s25, 0
	s_add_i32 s75, s78, s30
	global_load_lds_dwordx4 v[198:199], off
	v_lshl_add_u64 v[244:245], s[76:77], 0, v[136:137]
	s_mov_b32 m0, s75
	v_lshl_add_u64 v[246:247], s[26:27], 0, v[134:135]
	global_load_lds_dwordx4 v[244:245], off
	v_lshl_add_u64 v[244:245], s[76:77], 0, v[132:133]
	s_add_i32 m0, s75, 0x2000
	s_nop 0
	global_load_lds_dwordx4 v[244:245], off
	v_lshl_add_u64 v[244:245], s[26:27], 0, v[138:139]
	s_mov_b32 m0, s31
	s_nop 0
	global_load_lds_dwordx4 v[244:245], off
	s_mov_b32 m0, s34
	s_nop 0
	global_load_lds_dwordx4 v[246:247], off
	s_waitcnt vmcnt(8)
	s_waitcnt lgkmcnt(0)
	s_setprio 1
	s_barrier
; #define PG8_STAGE(bufoff, gbase, voff) do { _Pragma("unroll") for (int _i = 0; _i < 2; ++_i) \
;         __builtin_amdgcn_global_load_lds((const unsigned*)((const char*)(gbase) + (voff)[_i]), (LAS unsigned*)(lds + (bufoff) + ldsw + _i * 8192), 16, 0, 0); } while (0)
; #define PG8_LDA(dst, b, h) do { _Pragma("unroll") for (int m = 0; m < 4; ++m) _Pragma("unroll") for (int k = 0; k < 2; ++k) dst[m][k] = *(const LAS bf16x8*)(lds + PG8_SA(b, h) + aoff + m * 2048 + k * 1024); } while (0)
; #define PG8_LDB(dst, b, h) do { _Pragma("unroll") for (int n = 0; n < 2; ++n) _Pragma("unroll") for (int k = 0; k < 2; ++k) dst[n][k] = *(const LAS bf16x8*)(lds + PG8_SB(b, h) + boff + n * 2048 + k * 1024); } while (0)
; #define PG8_MMA(ai, bj, At, Bt) do { __builtin_amdgcn_s_setprio(1); _Pragma("unroll") for (int m = 0; m < 4; ++m) _Pragma("unroll") for (int n = 0; n < 2; ++n) _Pragma("unroll") for (int k = 0; k < 2; ++k) \
;         acc[ai][bj][m][n] = __builtin_amdgcn_mfma_f32_16x16x32_bf16(Bt[n][k], At[m][k], acc[ai][bj][m][n], 0, 0, 0); __builtin_amdgcn_s_setprio(0); } while (0)
; #define PG8_WAIT_V(n) asm volatile("s_waitcnt vmcnt(" #n ")" ::: "memory")
; #define PG8_WAIT_L(n) asm volatile("s_waitcnt lgkmcnt(" #n ")" ::: "memory")
; #define PG8_BAR __builtin_amdgcn_s_barrier()
; #define PG8_SCHED __builtin_amdgcn_sched_barrier(0)
; template <class Epi>
; __device__ __forceinline__ void gemm_phase(LAS unsigned char* lds, const Gemm g, const StaticOrder& S, const Epi& E) {
;     ...
;             PG8_WAIT_V(8); PG8_WAIT_L(0); PG8_BAR; PG8_MMA(1, 0, At, B0); PG8_MMA(1, 1, At, B1); PG8_BAR; PG8_SCHED;
;             PG8_LDB(B0, 1, 0); PG8_LDB(B1, 1, 1); PG8_SCHED; PG8_LDA(At, 1, 0); PG8_STAGE(PG8_SA(0, 1), a2 + hstep, voffA);
;             PG8_WAIT_V(8); PG8_WAIT_L(0); PG8_BAR; PG8_MMA(0, 0, At, B0); PG8_MMA(0, 1, At, B1); PG8_BAR; PG8_SCHED;
	v_mfma_f32_16x16x32_bf16 v[64:67], v[158:161], v[212:215], v[64:67]
	v_mfma_f32_16x16x32_bf16 v[60:63], v[170:173], v[212:215], v[60:63]
	v_mfma_f32_16x16x32_bf16 v[48:51], v[158:161], v[220:223], v[48:51]
	v_mfma_f32_16x16x32_bf16 v[44:47], v[170:173], v[220:223], v[44:47]
	v_mfma_f32_16x16x32_bf16 v[32:35], v[158:161], v[228:231], v[32:35]
	v_mfma_f32_16x16x32_bf16 v[28:31], v[170:173], v[228:231], v[28:31]
	v_mfma_f32_16x16x32_bf16 v[16:19], v[158:161], v[236:239], v[16:19]
	v_mfma_f32_16x16x32_bf16 v[12:15], v[170:173], v[236:239], v[12:15]
	v_mfma_f32_16x16x32_bf16 v[64:67], v[166:169], v[216:219], v[64:67]
	v_mfma_f32_16x16x32_bf16 v[60:63], v[174:177], v[216:219], v[60:63]
	v_mfma_f32_16x16x32_bf16 v[48:51], v[166:169], v[224:227], v[48:51]
	v_mfma_f32_16x16x32_bf16 v[44:47], v[174:177], v[224:227], v[44:47]
	v_mfma_f32_16x16x32_bf16 v[32:35], v[166:169], v[232:235], v[32:35]
	v_mfma_f32_16x16x32_bf16 v[28:31], v[174:177], v[232:235], v[28:31]
	v_mfma_f32_16x16x32_bf16 v[16:19], v[166:169], v[240:243], v[16:19]
	v_mfma_f32_16x16x32_bf16 v[12:15], v[174:177], v[240:243], v[12:15]
	s_setprio 0
	s_setprio 1
	v_mfma_f32_16x16x32_bf16 v[56:59], v[178:181], v[212:215], v[56:59]
	v_mfma_f32_16x16x32_bf16 v[52:55], v[186:189], v[212:215], v[52:55]
	v_mfma_f32_16x16x32_bf16 v[40:43], v[178:181], v[220:223], v[40:43]
	v_mfma_f32_16x16x32_bf16 v[36:39], v[186:189], v[220:223], v[36:39]
	v_mfma_f32_16x16x32_bf16 v[24:27], v[178:181], v[228:231], v[24:27]
	v_mfma_f32_16x16x32_bf16 v[20:23], v[186:189], v[228:231], v[20:23]
	v_mfma_f32_16x16x32_bf16 v[8:11], v[178:181], v[236:239], v[8:11]
	v_mfma_f32_16x16x32_bf16 v[4:7], v[186:189], v[236:239], v[4:7]
	v_mfma_f32_16x16x32_bf16 v[56:59], v[182:185], v[216:219], v[56:59]
	v_mfma_f32_16x16x32_bf16 v[52:55], v[190:193], v[216:219], v[52:55]
	v_mfma_f32_16x16x32_bf16 v[40:43], v[182:185], v[224:227], v[40:43]
	v_mfma_f32_16x16x32_bf16 v[36:39], v[190:193], v[224:227], v[36:39]
	v_mfma_f32_16x16x32_bf16 v[24:27], v[182:185], v[232:235], v[24:27]
	v_mfma_f32_16x16x32_bf16 v[20:23], v[190:193], v[232:235], v[20:23]
	v_mfma_f32_16x16x32_bf16 v[8:11], v[182:185], v[240:243], v[8:11]
	v_mfma_f32_16x16x32_bf16 v[4:7], v[190:193], v[240:243], v[4:7]
	s_barrier
	s_setprio 0
	s_add_i32 s75, 0, 0x18000
	s_add_i32 s76, 0, 0x1c000
	v_add_u32_e32 v174, s75, v147
	v_add_u32_e32 v190, s76, v147
	ds_read_b128 v[158:161], v174
	ds_read_b128 v[166:169], v174 offset:1024
	ds_read_b128 v[170:173], v174 offset:2048
	ds_read_b128 v[174:177], v174 offset:3072
	ds_read_b128 v[178:181], v190
	ds_read_b128 v[182:185], v190 offset:1024
	ds_read_b128 v[186:189], v190 offset:2048
	ds_read_b128 v[190:193], v190 offset:3072
	s_add_u32 s26, s26, 0x200000
	s_addc_u32 s27, s27, 0
	s_mov_b32 m0, s35
	v_lshl_add_u64 v[248:249], s[26:27], 0, v[138:139]
	ds_read_b128 v[212:215], v165 offset:32768
	ds_read_b128 v[216:219], v165 offset:33792
	ds_read_b128 v[220:223], v165 offset:34816
	ds_read_b128 v[224:227], v165 offset:35840
	ds_read_b128 v[228:231], v165 offset:36864
	ds_read_b128 v[232:235], v165 offset:37888
	ds_read_b128 v[236:239], v165 offset:38912
	ds_read_b128 v[240:243], v165 offset:39936
	global_load_lds_dwordx4 v[248:249], off
	v_lshl_add_u64 v[248:249], s[26:27], 0, v[134:135]
	s_mov_b32 m0, s36
	s_nop 0
	global_load_lds_dwordx4 v[248:249], off
	s_waitcnt vmcnt(8)
	s_waitcnt lgkmcnt(0)
	s_setprio 1
	s_barrier
	v_mfma_f32_16x16x32_bf16 v[128:131], v[158:161], v[212:215], v[128:131]
	v_mfma_f32_16x16x32_bf16 v[124:127], v[170:173], v[212:215], v[124:127]
	v_mfma_f32_16x16x32_bf16 v[112:115], v[158:161], v[220:223], v[112:115]
	v_mfma_f32_16x16x32_bf16 v[108:111], v[170:173], v[220:223], v[108:111]
	v_mfma_f32_16x16x32_bf16 v[96:99], v[158:161], v[228:231], v[96:99]
	v_mfma_f32_16x16x32_bf16 v[92:95], v[170:173], v[228:231], v[92:95]
	v_mfma_f32_16x16x32_bf16 v[80:83], v[158:161], v[236:239], v[80:83]
	v_mfma_f32_16x16x32_bf16 v[76:79], v[170:173], v[236:239], v[76:79]
	v_mfma_f32_16x16x32_bf16 v[128:131], v[166:169], v[216:219], v[128:131]
	v_mfma_f32_16x16x32_bf16 v[124:127], v[174:177], v[216:219], v[124:127]
	v_mfma_f32_16x16x32_bf16 v[112:115], v[166:169], v[224:227], v[112:115]
	v_mfma_f32_16x16x32_bf16 v[108:111], v[174:177], v[224:227], v[108:111]
	v_mfma_f32_16x16x32_bf16 v[96:99], v[166:169], v[232:235], v[96:99]
	v_mfma_f32_16x16x32_bf16 v[92:95], v[174:177], v[232:235], v[92:95]
	v_mfma_f32_16x16x32_bf16 v[80:83], v[166:169], v[240:243], v[80:83]
	v_mfma_f32_16x16x32_bf16 v[76:79], v[174:177], v[240:243], v[76:79]
	s_setprio 0
	s_setprio 1
	v_mfma_f32_16x16x32_bf16 v[120:123], v[178:181], v[212:215], v[120:123]
	v_mfma_f32_16x16x32_bf16 v[116:119], v[186:189], v[212:215], v[116:119]
	v_mfma_f32_16x16x32_bf16 v[104:107], v[178:181], v[220:223], v[104:107]
	v_mfma_f32_16x16x32_bf16 v[100:103], v[186:189], v[220:223], v[100:103]
	v_mfma_f32_16x16x32_bf16 v[88:91], v[178:181], v[228:231], v[88:91]
	v_mfma_f32_16x16x32_bf16 v[84:87], v[186:189], v[228:231], v[84:87]
	v_mfma_f32_16x16x32_bf16 v[72:75], v[178:181], v[236:239], v[72:75]
	v_mfma_f32_16x16x32_bf16 v[68:71], v[186:189], v[236:239], v[68:71]
	v_mfma_f32_16x16x32_bf16 v[120:123], v[182:185], v[216:219], v[120:123]
	v_mfma_f32_16x16x32_bf16 v[116:119], v[190:193], v[216:219], v[116:119]
	v_mfma_f32_16x16x32_bf16 v[104:107], v[182:185], v[224:227], v[104:107]
	v_mfma_f32_16x16x32_bf16 v[100:103], v[190:193], v[224:227], v[100:103]
	v_mfma_f32_16x16x32_bf16 v[88:91], v[182:185], v[232:235], v[88:91]
	v_mfma_f32_16x16x32_bf16 v[84:87], v[190:193], v[232:235], v[84:87]
	v_mfma_f32_16x16x32_bf16 v[72:75], v[182:185], v[240:243], v[72:75]
	v_mfma_f32_16x16x32_bf16 v[68:71], v[190:193], v[240:243], v[68:71]
	s_barrier
; #define PG8_STAGE(bufoff, gbase, voff) do { _Pragma("unroll") for (int _i = 0; _i < 2; ++_i) \
;         __builtin_amdgcn_global_load_lds((const unsigned*)((const char*)(gbase) + (voff)[_i]), (LAS unsigned*)(lds + (bufoff) + ldsw + _i * 8192), 16, 0, 0); } while (0)
; #define PG8_LDA(dst, b, h) do { _Pragma("unroll") for (int m = 0; m < 4; ++m) _Pragma("unroll") for (int k = 0; k < 2; ++k) dst[m][k] = *(const LAS bf16x8*)(lds + PG8_SA(b, h) + aoff + m * 2048 + k * 1024); } while (0)
; #define PG8_MMA(ai, bj, At, Bt) do { __builtin_amdgcn_s_setprio(1); _Pragma("unroll") for (int m = 0; m < 4; ++m) _Pragma("unroll") for (int n = 0; n < 2; ++n) _Pragma("unroll") for (int k = 0; k < 2; ++k) \
;         acc[ai][bj][m][n] = __builtin_amdgcn_mfma_f32_16x16x32_bf16(Bt[n][k], At[m][k], acc[ai][bj][m][n], 0, 0, 0); __builtin_amdgcn_s_setprio(0); } while (0)
; #define PG8_WAIT_V(n) asm volatile("s_waitcnt vmcnt(" #n ")" ::: "memory")
; #define PG8_WAIT_L(n) asm volatile("s_waitcnt lgkmcnt(" #n ")" ::: "memory")
; #define PG8_BAR __builtin_amdgcn_s_barrier()
; #define PG8_SCHED __builtin_amdgcn_sched_barrier(0)
; template <class Epi>
; __device__ __forceinline__ void gemm_phase(LAS unsigned char* lds, const Gemm g, const StaticOrder& S, const Epi& E) {
;     ...
;             PG8_LDA(At, 1, 1); PG8_STAGE(PG8_SB(1, 0), b3, voffB); PG8_STAGE(PG8_SB(1, 1), b3 + hstep, voffB); PG8_STAGE(PG8_SA(1, 0), a3, voffA);
;             PG8_WAIT_V(8); PG8_WAIT_L(0); PG8_BAR; PG8_MMA(1, 0, At, B0); PG8_MMA(1, 1, At, B1); PG8_BAR; PG8_SCHED;
;         }
	s_setprio 0
	s_add_i32 s26, s75, s30
	v_lshl_add_u64 v[162:163], v[162:163], 0, s[68:69]
	s_mov_b32 m0, s26
	ds_read_b128 v[212:215], v165 offset:49152
	ds_read_b128 v[216:219], v165 offset:50176
	ds_read_b128 v[220:223], v165 offset:51200
	ds_read_b128 v[224:227], v165 offset:52224
	ds_read_b128 v[228:231], v165 offset:53248
	ds_read_b128 v[232:235], v165 offset:54272
	ds_read_b128 v[236:239], v165 offset:55296
	ds_read_b128 v[240:243], v165 offset:56320
	global_load_lds_dwordx4 v[162:163], off
	s_add_i32 m0, s26, 0x2000
	s_add_u32 s24, s24, 0x200080
	v_lshl_add_u64 v[162:163], v[198:199], 0, s[68:69]
	s_addc_u32 s25, s25, 0
	s_add_i32 s26, s76, s30
	global_load_lds_dwordx4 v[162:163], off
	v_lshl_add_u64 v[162:163], s[24:25], 0, v[136:137]
	s_mov_b32 m0, s26
	s_nop 0
	global_load_lds_dwordx4 v[162:163], off
	v_lshl_add_u64 v[162:163], s[24:25], 0, v[132:133]
	s_add_i32 m0, s26, 0x2000
	s_nop 0
	global_load_lds_dwordx4 v[162:163], off
	v_lshl_add_u64 v[162:163], v[244:245], 0, s[68:69]
	s_mov_b32 m0, s38
	s_nop 0
	global_load_lds_dwordx4 v[162:163], off
	v_lshl_add_u64 v[162:163], v[246:247], 0, s[68:69]
	s_mov_b32 m0, s39
	s_nop 0
	global_load_lds_dwordx4 v[162:163], off
	s_waitcnt vmcnt(8)
	s_waitcnt lgkmcnt(0)
	s_setprio 1
	s_barrier
	v_mfma_f32_16x16x32_bf16 v[64:67], v[158:161], v[212:215], v[64:67]
	v_mfma_f32_16x16x32_bf16 v[60:63], v[170:173], v[212:215], v[60:63]
	v_mfma_f32_16x16x32_bf16 v[48:51], v[158:161], v[220:223], v[48:51]
	v_mfma_f32_16x16x32_bf16 v[44:47], v[170:173], v[220:223], v[44:47]
	v_mfma_f32_16x16x32_bf16 v[32:35], v[158:161], v[228:231], v[32:35]
	v_mfma_f32_16x16x32_bf16 v[28:31], v[170:173], v[228:231], v[28:31]
	v_mfma_f32_16x16x32_bf16 v[16:19], v[158:161], v[236:239], v[16:19]
	v_mfma_f32_16x16x32_bf16 v[12:15], v[170:173], v[236:239], v[12:15]
	v_mfma_f32_16x16x32_bf16 v[64:67], v[166:169], v[216:219], v[64:67]
	v_mfma_f32_16x16x32_bf16 v[60:63], v[174:177], v[216:219], v[60:63]
	v_mfma_f32_16x16x32_bf16 v[48:51], v[166:169], v[224:227], v[48:51]
	v_mfma_f32_16x16x32_bf16 v[44:47], v[174:177], v[224:227], v[44:47]
	v_mfma_f32_16x16x32_bf16 v[32:35], v[166:169], v[232:235], v[32:35]
	v_mfma_f32_16x16x32_bf16 v[28:31], v[174:177], v[232:235], v[28:31]
	v_mfma_f32_16x16x32_bf16 v[16:19], v[166:169], v[240:243], v[16:19]
	v_mfma_f32_16x16x32_bf16 v[12:15], v[174:177], v[240:243], v[12:15]
	s_setprio 0
	s_setprio 1
	v_mfma_f32_16x16x32_bf16 v[56:59], v[178:181], v[212:215], v[56:59]
	v_mfma_f32_16x16x32_bf16 v[52:55], v[186:189], v[212:215], v[52:55]
	v_mfma_f32_16x16x32_bf16 v[40:43], v[178:181], v[220:223], v[40:43]
	v_mfma_f32_16x16x32_bf16 v[36:39], v[186:189], v[220:223], v[36:39]
	v_mfma_f32_16x16x32_bf16 v[24:27], v[178:181], v[228:231], v[24:27]
	v_mfma_f32_16x16x32_bf16 v[20:23], v[186:189], v[228:231], v[20:23]
	v_mfma_f32_16x16x32_bf16 v[8:11], v[178:181], v[236:239], v[8:11]
	v_mfma_f32_16x16x32_bf16 v[4:7], v[186:189], v[236:239], v[4:7]
	v_mfma_f32_16x16x32_bf16 v[56:59], v[182:185], v[216:219], v[56:59]
	v_mfma_f32_16x16x32_bf16 v[52:55], v[190:193], v[216:219], v[52:55]
	v_mfma_f32_16x16x32_bf16 v[40:43], v[182:185], v[224:227], v[40:43]
	v_mfma_f32_16x16x32_bf16 v[36:39], v[190:193], v[224:227], v[36:39]
	v_mfma_f32_16x16x32_bf16 v[24:27], v[182:185], v[232:235], v[24:27]
	v_mfma_f32_16x16x32_bf16 v[20:23], v[190:193], v[232:235], v[20:23]
	v_mfma_f32_16x16x32_bf16 v[8:11], v[182:185], v[240:243], v[8:11]
	v_mfma_f32_16x16x32_bf16 v[4:7], v[190:193], v[240:243], v[4:7]
	s_barrier
	s_setprio 0
	s_add_i32 s74, s74, 2
	s_add_u32 s22, s22, 0x100
	s_addc_u32 s23, s23, 0
	s_add_u32 s60, s60, 0x100
	s_addc_u32 s61, s61, 0
	s_cmpk_gt_u32 s74, 0x7d
	s_cbranch_scc0 .LBB0_1972
	s_and_b64 vcc, exec, s[12:13]
	s_cbranch_vccz .LBB0_1975
	s_barrier
